# speedup vs baseline: 1.1008x; 1.0113x over previous
; #define WAITV8(n) asm volatile("s_waitcnt vmcnt(" #n ")" ::: "memory")
; #define BAR8 __builtin_amdgcn_s_barrier()
;   DEV void tile_begin(int brow, char* shm, int tid) const { rstd_tile_begin(ss, brow, shm, tid); }
;   DEV void tile_begin(int brow, char* shm, int tid) const { rstd_tile_begin(ss, brow, shm, tid); }
; template <class Epi>
; DEV void gemm_tile8(char* shm, const u16* __restrict__ A, const u16* __restrict__ Bt, int K, int brow, int bcol, Epi& epi) {
;     ...
;   { int r_, c_; stage_rc<2>(wid * 1024 + lane * 16, r_, c_); so0 = r_ * K + c_; }
;   const int wids = __builtin_amdgcn_readfirstlane(wid);
;   const int la = lds_byte<2>(wr * 64 + fr, fq * 8), lb = lds_byte<2>(wc * 32 + fr, fq * 8);
;   f32x4 acc[2][2][4][2];
; #pragma unroll
;   for (int a = 0; a < 2; ++a)
; #pragma unroll
;     for (int b = 0; b < 2; ++b)
; #pragma unroll
;       for (int m = 0; m < 4; ++m)
; #pragma unroll
;         for (int n = 0; n < 2; ++n) acc[a][b][m][n] = f32x4{0.f, 0.f, 0.f, 0.f};
;   bf16x8 At[4][2], B0[2][2], B1[2][2];
;   const int nt = K / BK;
;   epi.tile_begin(brow, shm, tid);
;     ...
;   WAITV8(0);
;   STAGE8(SB8(0, 0), Bt, bcol, 0); STAGE8(SA8(0, 0), A, brow, 0);
;   STAGE8(SB8(0, 1), Bt, bcol + HALF, 0); STAGE8(SA8(0, 1), A, brow + HALF, 0);
;   if (wrs == 1) BAR8;
;   WAITV8(4); BAR8;
;   STAGE8(SB8(1, 0), Bt, bcol, 1); STAGE8(SA8(1, 0), A, brow, 1); STAGE8(SB8(1, 1), Bt, bcol + HALF, 1);
;   WAITV8(6); BAR8;
.LBB0_388:
	v_and_b32_e32 v12, 15, v8
	v_and_b32_e32 v13, 48, v8
	v_lshlrev_b32_e32 v8, 2, v8
	v_lshlrev_b32_e32 v12, 6, v12
	v_and_b32_e32 v8, 32, v8
	v_or_b32_e32 v14, v12, v13
	v_bitop3_b32 v12, v12, v8, v13 bitop3:0x36
	v_lshlrev_b32_e32 v13, 12, v6
	s_movk_i32 s24, 0x3000
	v_and_or_b32 v133, v13, s24, v12
	s_mov_b64 s[24:25], 0x80
	s_add_i32 s85, s7, 0x18000
	v_lshl_add_u64 v[12:13], v[0:1], 0, s[24:25]
	s_mov_b32 m0, s85
	s_mov_b64 s[94:95], 0x20080
	s_add_i32 s90, s7, 0x1a000
	s_waitcnt vmcnt(4)
	s_barrier
	global_load_lds_dwordx4 v[12:13], off
	v_lshl_add_u64 v[0:1], v[0:1], 0, s[94:95]
	s_mov_b32 m0, s90
	s_add_i32 s91, s7, 0x8000
	global_load_lds_dwordx4 v[0:1], off
	v_lshl_add_u64 v[0:1], v[2:3], 0, s[24:25]
	s_mov_b32 m0, s91
	s_add_i32 s92, s7, 0xa000
	global_load_lds_dwordx4 v[0:1], off
	v_lshl_add_u64 v[0:1], v[2:3], 0, s[94:95]
	s_mov_b32 m0, s92
	s_add_i32 s93, s7, 0x1c000
	global_load_lds_dwordx4 v[0:1], off
	v_lshl_add_u64 v[0:1], v[4:5], 0, s[24:25]
	s_mov_b32 m0, s93
	s_movk_i32 s24, 0x3fc0
	global_load_lds_dwordx4 v[0:1], off
	v_lshl_add_u64 v[0:1], v[4:5], 0, s[94:95]
	s_add_i32 s94, s7, 0x1e000
	s_mov_b32 m0, s94
	s_add_u32 s10, s38, s10
	global_load_lds_dwordx4 v[0:1], off
	v_mul_lo_u32 v0, v9, s24
	v_or_b32_e32 v0, v10, v0
	v_lshlrev_b32_e32 v1, 5, v6
	v_add3_u32 v0, v0, v11, v1
	s_waitcnt vmcnt(6)
	v_ashrrev_i32_e32 v1, 31, v0
	s_addc_u32 s11, s39, s11
	v_lshlrev_b32_e32 v7, 13, v7
	v_lshlrev_b64 v[130:131], 1, v[0:1]
	s_add_u32 s24, s38, s26
	v_mov_b32_e32 v0, 0
	v_bitop3_b32 v132, v14, v7, v8 bitop3:0xde
	s_addc_u32 s25, s39, s27
	s_mov_b32 s26, -2
	v_mov_b32_e32 v1, v0
	v_mov_b32_e32 v2, v0
	v_mov_b32_e32 v3, v0
	v_mov_b32_e32 v4, v0
	v_mov_b32_e32 v5, v0
	v_mov_b32_e32 v6, v0
	v_mov_b32_e32 v7, v0
	v_mov_b32_e32 v8, v0
	v_mov_b32_e32 v9, v0
	v_mov_b32_e32 v10, v0
	v_mov_b32_e32 v11, v0
	v_mov_b32_e32 v12, v0
	v_mov_b32_e32 v13, v0
	v_mov_b32_e32 v14, v0
	v_mov_b32_e32 v15, v0
	v_mov_b32_e32 v16, v0
	v_mov_b32_e32 v17, v0
	v_mov_b32_e32 v18, v0
	v_mov_b32_e32 v19, v0
	v_mov_b32_e32 v20, v0
	v_mov_b32_e32 v21, v0
	v_mov_b32_e32 v22, v0
	v_mov_b32_e32 v23, v0
	v_mov_b32_e32 v24, v0
	v_mov_b32_e32 v25, v0
	v_mov_b32_e32 v26, v0
	v_mov_b32_e32 v27, v0
	v_mov_b32_e32 v28, v0
	v_mov_b32_e32 v29, v0
	v_mov_b32_e32 v30, v0
	v_mov_b32_e32 v31, v0
	v_mov_b32_e32 v32, v0
	v_mov_b32_e32 v33, v0
	v_mov_b32_e32 v34, v0
	v_mov_b32_e32 v35, v0
	v_mov_b32_e32 v36, v0
	v_mov_b32_e32 v37, v0
	v_mov_b32_e32 v38, v0
	v_mov_b32_e32 v39, v0
	v_mov_b32_e32 v40, v0
	v_mov_b32_e32 v41, v0
	v_mov_b32_e32 v42, v0
	v_mov_b32_e32 v43, v0
	v_mov_b32_e32 v44, v0
	v_mov_b32_e32 v45, v0
	v_mov_b32_e32 v46, v0
	v_mov_b32_e32 v47, v0
	v_mov_b32_e32 v48, v0
	v_mov_b32_e32 v49, v0
	v_mov_b32_e32 v50, v0
	v_mov_b32_e32 v51, v0
	v_mov_b32_e32 v52, v0
	v_mov_b32_e32 v53, v0
	v_mov_b32_e32 v54, v0
	v_mov_b32_e32 v55, v0
	v_mov_b32_e32 v56, v0
	v_mov_b32_e32 v57, v0
	v_mov_b32_e32 v58, v0
	v_mov_b32_e32 v59, v0
	v_mov_b32_e32 v60, v0
	v_mov_b32_e32 v61, v0
	v_mov_b32_e32 v62, v0
	v_mov_b32_e32 v63, v0
	v_mov_b32_e32 v64, v0
	v_mov_b32_e32 v65, v0
	v_mov_b32_e32 v66, v0
	v_mov_b32_e32 v67, v0
	v_mov_b32_e32 v68, v0
	v_mov_b32_e32 v69, v0
	v_mov_b32_e32 v70, v0
	v_mov_b32_e32 v71, v0
	v_mov_b32_e32 v72, v0
	v_mov_b32_e32 v73, v0
	v_mov_b32_e32 v74, v0
	v_mov_b32_e32 v75, v0
	v_mov_b32_e32 v76, v0
	v_mov_b32_e32 v77, v0
	v_mov_b32_e32 v78, v0
	v_mov_b32_e32 v79, v0
	v_mov_b32_e32 v80, v0
	v_mov_b32_e32 v81, v0
	v_mov_b32_e32 v82, v0
	v_mov_b32_e32 v83, v0
	v_mov_b32_e32 v84, v0
	v_mov_b32_e32 v85, v0
	v_mov_b32_e32 v86, v0
	v_mov_b32_e32 v87, v0
	v_mov_b32_e32 v88, v0
	v_mov_b32_e32 v89, v0
	v_mov_b32_e32 v90, v0
	v_mov_b32_e32 v91, v0
	v_mov_b32_e32 v92, v0
	v_mov_b32_e32 v93, v0
	v_mov_b32_e32 v94, v0
	v_mov_b32_e32 v95, v0
	v_mov_b32_e32 v96, v0
	v_mov_b32_e32 v97, v0
	v_mov_b32_e32 v98, v0
	v_mov_b32_e32 v99, v0
	v_mov_b32_e32 v100, v0
	v_mov_b32_e32 v101, v0
	v_mov_b32_e32 v102, v0
	v_mov_b32_e32 v103, v0
	v_mov_b32_e32 v104, v0
	v_mov_b32_e32 v105, v0
	v_mov_b32_e32 v106, v0
	v_mov_b32_e32 v107, v0
	v_mov_b32_e32 v108, v0
	v_mov_b32_e32 v109, v0
	v_mov_b32_e32 v110, v0
	v_mov_b32_e32 v111, v0
	v_mov_b32_e32 v112, v0
	v_mov_b32_e32 v113, v0
	v_mov_b32_e32 v114, v0
	v_mov_b32_e32 v115, v0
	v_mov_b32_e32 v116, v0
	v_mov_b32_e32 v117, v0
	v_mov_b32_e32 v118, v0
	v_mov_b32_e32 v119, v0
	v_mov_b32_e32 v120, v0
	v_mov_b32_e32 v121, v0
	v_mov_b32_e32 v122, v0
	v_mov_b32_e32 v123, v0
	v_mov_b32_e32 v124, v0
	v_mov_b32_e32 v125, v0
	v_mov_b32_e32 v126, v0
	v_mov_b32_e32 v127, v0
	s_mov_b64 vcc, 0x19cc0080
	s_mov_b64 s[14:15], 0x19ce0080
	s_mov_b64 s[18:19], 0x19cc0100
	s_mov_b64 s[22:23], 0x19ce0100
	s_barrier

; #define WAITV8(n) asm volatile("s_waitcnt vmcnt(" #n ")" ::: "memory")
; #define BAR8 __builtin_amdgcn_s_barrier()
;   DEV void tile_begin(int brow, char* shm, int tid) const { rstd_tile_begin(ss, brow, shm, tid); }
;   DEV void tile_begin(int brow, char* shm, int tid) const { rstd_tile_begin(ss, brow, shm, tid); }
; template <class Epi>
; DEV void gemm_tile8(char* shm, const u16* __restrict__ A, const u16* __restrict__ Bt, int K, int brow, int bcol, Epi& epi) {
;     ...
;   { int r_, c_; stage_rc<2>(wid * 1024 + lane * 16, r_, c_); so0 = r_ * K + c_; }
;   const int wids = __builtin_amdgcn_readfirstlane(wid);
;   const int la = lds_byte<2>(wr * 64 + fr, fq * 8), lb = lds_byte<2>(wc * 32 + fr, fq * 8);
;   f32x4 acc[2][2][4][2];
; #pragma unroll
;   for (int a = 0; a < 2; ++a)
; #pragma unroll
;     for (int b = 0; b < 2; ++b)
; #pragma unroll
;       for (int m = 0; m < 4; ++m)
; #pragma unroll
;         for (int n = 0; n < 2; ++n) acc[a][b][m][n] = f32x4{0.f, 0.f, 0.f, 0.f};
;   bf16x8 At[4][2], B0[2][2], B1[2][2];
;   const int nt = K / BK;
;   epi.tile_begin(brow, shm, tid);
;     ...
;   WAITV8(0);
;   STAGE8(SB8(0, 0), Bt, bcol, 0); STAGE8(SA8(0, 0), A, brow, 0);
;   STAGE8(SB8(0, 1), Bt, bcol + HALF, 0); STAGE8(SA8(0, 1), A, brow + HALF, 0);
;   if (wrs == 1) BAR8;
;   WAITV8(4); BAR8;
;   STAGE8(SB8(1, 0), Bt, bcol, 1); STAGE8(SA8(1, 0), A, brow, 1); STAGE8(SB8(1, 1), Bt, bcol + HALF, 1);
;   WAITV8(6); BAR8;
.LBB0_423:
	v_and_b32_e32 v12, 15, v10
	v_and_b32_e32 v13, 48, v10
	v_lshlrev_b32_e32 v10, 2, v10
	v_lshlrev_b32_e32 v12, 6, v12
	v_and_b32_e32 v10, 32, v10
	v_or_b32_e32 v14, v12, v13
	v_bitop3_b32 v12, v12, v10, v13 bitop3:0x36
	v_lshlrev_b32_e32 v13, 12, v6
	s_movk_i32 s20, 0x3000
	v_lshlrev_b32_e32 v11, 13, v11
	v_and_or_b32 v133, v13, s20, v12
	s_mov_b64 s[20:21], 0x80
	s_add_i32 s85, s54, 0x18000
	v_bitop3_b32 v132, v14, v11, v10 bitop3:0xde
	v_lshl_add_u64 v[10:11], v[0:1], 0, s[20:21]
	s_mov_b32 m0, s85
	s_mov_b64 s[14:15], 0x58080
	s_add_i32 s90, s54, 0x1a000
	s_waitcnt vmcnt(4)
	s_barrier
	global_load_lds_dwordx4 v[10:11], off
	v_lshl_add_u64 v[0:1], v[0:1], 0, s[14:15]
	s_mov_b32 m0, s90
	s_add_i32 s91, s54, 0x8000
	global_load_lds_dwordx4 v[0:1], off
	v_lshl_add_u64 v[0:1], v[2:3], 0, s[20:21]
	s_mov_b32 m0, s91
	s_add_i32 s92, s54, 0xa000
	global_load_lds_dwordx4 v[0:1], off
	v_lshl_add_u64 v[0:1], v[2:3], 0, s[14:15]
	s_mov_b32 m0, s92
	s_add_i32 s93, s54, 0x1c000
	global_load_lds_dwordx4 v[0:1], off
	v_lshl_add_u64 v[0:1], v[4:5], 0, s[20:21]
	s_mov_b32 m0, s93
	s_add_i32 s94, s54, 0x1e000
	global_load_lds_dwordx4 v[0:1], off
	v_lshl_add_u64 v[0:1], v[4:5], 0, s[14:15]
	s_mov_b32 m0, s94
	s_mov_b32 s20, 0xafc0
	global_load_lds_dwordx4 v[0:1], off
	v_mul_lo_u32 v0, v8, s20
	v_or_b32_e32 v0, v9, v0
	v_mul_u32_u24_e32 v1, 0xb00, v7
	v_lshlrev_b32_e32 v2, 5, v6
	v_add3_u32 v0, v0, v1, v2
	s_add_u32 s20, s38, s23
	s_waitcnt vmcnt(6)
	v_ashrrev_i32_e32 v1, 31, v0
	s_addc_u32 s21, s39, s22
	v_lshlrev_b64 v[130:131], 1, v[0:1]
	s_add_u32 s22, s38, s96
	v_mov_b32_e32 v0, 0
	s_addc_u32 s23, s39, s95
	s_mov_b32 s95, -2
	v_mov_b32_e32 v1, v0
	v_mov_b32_e32 v2, v0
	v_mov_b32_e32 v3, v0
	v_mov_b32_e32 v4, v0
	v_mov_b32_e32 v5, v0
	v_mov_b32_e32 v6, v0
	v_mov_b32_e32 v7, v0
	v_mov_b32_e32 v8, v0
	v_mov_b32_e32 v9, v0
	v_mov_b32_e32 v10, v0
	v_mov_b32_e32 v11, v0
	v_mov_b32_e32 v12, v0
	v_mov_b32_e32 v13, v0
	v_mov_b32_e32 v14, v0
	v_mov_b32_e32 v15, v0
	v_mov_b32_e32 v16, v0
	v_mov_b32_e32 v17, v0
	v_mov_b32_e32 v18, v0
	v_mov_b32_e32 v19, v0
	v_mov_b32_e32 v20, v0
	v_mov_b32_e32 v21, v0
	v_mov_b32_e32 v22, v0
	v_mov_b32_e32 v23, v0
	v_mov_b32_e32 v24, v0
	v_mov_b32_e32 v25, v0
	v_mov_b32_e32 v26, v0
	v_mov_b32_e32 v27, v0
	v_mov_b32_e32 v28, v0
	v_mov_b32_e32 v29, v0
	v_mov_b32_e32 v30, v0
	v_mov_b32_e32 v31, v0
	v_mov_b32_e32 v32, v0
	v_mov_b32_e32 v33, v0
	v_mov_b32_e32 v34, v0
	v_mov_b32_e32 v35, v0
	v_mov_b32_e32 v36, v0
	v_mov_b32_e32 v37, v0
	v_mov_b32_e32 v38, v0
	v_mov_b32_e32 v39, v0
	v_mov_b32_e32 v40, v0
	v_mov_b32_e32 v41, v0
	v_mov_b32_e32 v42, v0
	v_mov_b32_e32 v43, v0
	v_mov_b32_e32 v44, v0
	v_mov_b32_e32 v45, v0
	v_mov_b32_e32 v46, v0
	v_mov_b32_e32 v47, v0
	v_mov_b32_e32 v48, v0
	v_mov_b32_e32 v49, v0
	v_mov_b32_e32 v50, v0
	v_mov_b32_e32 v51, v0
	v_mov_b32_e32 v52, v0
	v_mov_b32_e32 v53, v0
	v_mov_b32_e32 v54, v0
	v_mov_b32_e32 v55, v0
	v_mov_b32_e32 v56, v0
	v_mov_b32_e32 v57, v0
	v_mov_b32_e32 v58, v0
	v_mov_b32_e32 v59, v0
	v_mov_b32_e32 v60, v0
	v_mov_b32_e32 v61, v0
	v_mov_b32_e32 v62, v0
	v_mov_b32_e32 v63, v0
	v_mov_b32_e32 v64, v0
	v_mov_b32_e32 v65, v0
	v_mov_b32_e32 v66, v0
	v_mov_b32_e32 v67, v0
	v_mov_b32_e32 v68, v0
	v_mov_b32_e32 v69, v0
	v_mov_b32_e32 v70, v0
	v_mov_b32_e32 v71, v0
	v_mov_b32_e32 v72, v0
	v_mov_b32_e32 v73, v0
	v_mov_b32_e32 v74, v0
	v_mov_b32_e32 v75, v0
	v_mov_b32_e32 v76, v0
	v_mov_b32_e32 v77, v0
	v_mov_b32_e32 v78, v0
	v_mov_b32_e32 v79, v0
	v_mov_b32_e32 v80, v0
	v_mov_b32_e32 v81, v0
	v_mov_b32_e32 v82, v0
	v_mov_b32_e32 v83, v0
	v_mov_b32_e32 v84, v0
	v_mov_b32_e32 v85, v0
	v_mov_b32_e32 v86, v0
	v_mov_b32_e32 v87, v0
	v_mov_b32_e32 v88, v0
	v_mov_b32_e32 v89, v0
	v_mov_b32_e32 v90, v0
	v_mov_b32_e32 v91, v0
	v_mov_b32_e32 v92, v0
	v_mov_b32_e32 v93, v0
	v_mov_b32_e32 v94, v0
	v_mov_b32_e32 v95, v0
	v_mov_b32_e32 v96, v0
	v_mov_b32_e32 v97, v0
	v_mov_b32_e32 v98, v0
	v_mov_b32_e32 v99, v0
	v_mov_b32_e32 v100, v0
	v_mov_b32_e32 v101, v0
	v_mov_b32_e32 v102, v0
	v_mov_b32_e32 v103, v0
	v_mov_b32_e32 v104, v0
	v_mov_b32_e32 v105, v0
	v_mov_b32_e32 v106, v0
	v_mov_b32_e32 v107, v0
	v_mov_b32_e32 v108, v0
	v_mov_b32_e32 v109, v0
	v_mov_b32_e32 v110, v0
	v_mov_b32_e32 v111, v0
	v_mov_b32_e32 v112, v0
	v_mov_b32_e32 v113, v0
	v_mov_b32_e32 v114, v0
	v_mov_b32_e32 v115, v0
	v_mov_b32_e32 v116, v0
	v_mov_b32_e32 v117, v0
	v_mov_b32_e32 v118, v0
	v_mov_b32_e32 v119, v0
	v_mov_b32_e32 v120, v0
	v_mov_b32_e32 v121, v0
	v_mov_b32_e32 v122, v0
	v_mov_b32_e32 v123, v0
	v_mov_b32_e32 v124, v0
	v_mov_b32_e32 v125, v0
	v_mov_b32_e32 v126, v0
	v_mov_b32_e32 v127, v0
	s_barrier

; #define WAITV8(n) asm volatile("s_waitcnt vmcnt(" #n ")" ::: "memory")
; #define BAR8 __builtin_amdgcn_s_barrier()
;   DEV void tile_begin(int brow, char* shm, int tid) const { rstd_tile_begin(ss, brow, shm, tid); }
;   DEV void tile_begin(int brow, char* shm, int tid) const { rstd_tile_begin(ss, brow, shm, tid); }
; template <class Epi>
; DEV void gemm_tile8(char* shm, const u16* __restrict__ A, const u16* __restrict__ Bt, int K, int brow, int bcol, Epi& epi) {
;     ...
;   { int r_, c_; stage_rc<2>(wid * 1024 + lane * 16, r_, c_); so0 = r_ * K + c_; }
;   const int wids = __builtin_amdgcn_readfirstlane(wid);
;   const int la = lds_byte<2>(wr * 64 + fr, fq * 8), lb = lds_byte<2>(wc * 32 + fr, fq * 8);
;   f32x4 acc[2][2][4][2];
; #pragma unroll
;   for (int a = 0; a < 2; ++a)
; #pragma unroll
;     for (int b = 0; b < 2; ++b)
; #pragma unroll
;       for (int m = 0; m < 4; ++m)
; #pragma unroll
;         for (int n = 0; n < 2; ++n) acc[a][b][m][n] = f32x4{0.f, 0.f, 0.f, 0.f};
;   bf16x8 At[4][2], B0[2][2], B1[2][2];
;   const int nt = K / BK;
;   epi.tile_begin(brow, shm, tid);
;     ...
;   WAITV8(0);
;   STAGE8(SB8(0, 0), Bt, bcol, 0); STAGE8(SA8(0, 0), A, brow, 0);
;   STAGE8(SB8(0, 1), Bt, bcol + HALF, 0); STAGE8(SA8(0, 1), A, brow + HALF, 0);
;   if (wrs == 1) BAR8;
;   WAITV8(4); BAR8;
;   STAGE8(SB8(1, 0), Bt, bcol, 1); STAGE8(SA8(1, 0), A, brow, 1); STAGE8(SB8(1, 1), Bt, bcol + HALF, 1);
;   WAITV8(6); BAR8;
.LBB0_467:
	v_and_b32_e32 v12, 15, v8
	v_and_b32_e32 v13, 48, v8
	v_lshlrev_b32_e32 v8, 2, v8
	v_lshlrev_b32_e32 v12, 6, v12
	v_and_b32_e32 v8, 32, v8
	v_or_b32_e32 v14, v12, v13
	v_bitop3_b32 v12, v12, v8, v13 bitop3:0x36
	v_lshlrev_b32_e32 v13, 12, v6
	s_movk_i32 s22, 0x3000
	v_and_or_b32 v133, v13, s22, v12
	s_mov_b64 s[22:23], 0x80
	s_add_i32 s81, s7, 0x18000
	v_lshl_add_u64 v[12:13], v[0:1], 0, s[22:23]
	s_mov_b32 m0, s81
	s_mov_b64 s[92:93], 0x20080
	s_add_i32 s84, s7, 0x1a000
	s_waitcnt vmcnt(4)
	s_barrier
	global_load_lds_dwordx4 v[12:13], off
	v_lshl_add_u64 v[0:1], v[0:1], 0, s[92:93]
	s_mov_b32 m0, s84
	s_add_i32 s85, s7, 0x8000
	global_load_lds_dwordx4 v[0:1], off
	v_lshl_add_u64 v[0:1], v[2:3], 0, s[22:23]
	s_mov_b32 m0, s85
	s_add_i32 s90, s7, 0xa000
	global_load_lds_dwordx4 v[0:1], off
	v_lshl_add_u64 v[0:1], v[2:3], 0, s[92:93]
	s_mov_b32 m0, s90
	s_add_i32 s91, s7, 0x1c000
	global_load_lds_dwordx4 v[0:1], off
	v_lshl_add_u64 v[0:1], v[4:5], 0, s[22:23]
	s_mov_b32 m0, s91
	s_movk_i32 s22, 0x3fc0
	global_load_lds_dwordx4 v[0:1], off
	v_lshl_add_u64 v[0:1], v[4:5], 0, s[92:93]
	s_add_i32 s92, s7, 0x1e000
	s_mov_b32 m0, s92
	s_add_u32 s10, s38, s10
	global_load_lds_dwordx4 v[0:1], off
	v_mul_lo_u32 v0, v9, s22
	v_or_b32_e32 v0, v10, v0
	v_lshlrev_b32_e32 v1, 5, v6
	v_add3_u32 v0, v0, v11, v1
	s_waitcnt vmcnt(6)
	v_ashrrev_i32_e32 v1, 31, v0
	s_addc_u32 s11, s39, s11
	v_lshlrev_b32_e32 v7, 13, v7
	v_lshlrev_b64 v[130:131], 1, v[0:1]
	s_add_u32 s22, s38, s24
	v_mov_b32_e32 v0, 0
	v_bitop3_b32 v132, v14, v7, v8 bitop3:0xde
	s_addc_u32 s23, s39, s25
	s_mov_b32 s24, -2
	v_mov_b32_e32 v1, v0
	v_mov_b32_e32 v2, v0
	v_mov_b32_e32 v3, v0
	v_mov_b32_e32 v4, v0
	v_mov_b32_e32 v5, v0
	v_mov_b32_e32 v6, v0
	v_mov_b32_e32 v7, v0
	v_mov_b32_e32 v8, v0
	v_mov_b32_e32 v9, v0
	v_mov_b32_e32 v10, v0
	v_mov_b32_e32 v11, v0
	v_mov_b32_e32 v12, v0
	v_mov_b32_e32 v13, v0
	v_mov_b32_e32 v14, v0
	v_mov_b32_e32 v15, v0
	v_mov_b32_e32 v16, v0
	v_mov_b32_e32 v17, v0
	v_mov_b32_e32 v18, v0
	v_mov_b32_e32 v19, v0
	v_mov_b32_e32 v20, v0
	v_mov_b32_e32 v21, v0
	v_mov_b32_e32 v22, v0
	v_mov_b32_e32 v23, v0
	v_mov_b32_e32 v24, v0
	v_mov_b32_e32 v25, v0
	v_mov_b32_e32 v26, v0
	v_mov_b32_e32 v27, v0
	v_mov_b32_e32 v28, v0
	v_mov_b32_e32 v29, v0
	v_mov_b32_e32 v30, v0
	v_mov_b32_e32 v31, v0
	v_mov_b32_e32 v32, v0
	v_mov_b32_e32 v33, v0
	v_mov_b32_e32 v34, v0
	v_mov_b32_e32 v35, v0
	v_mov_b32_e32 v36, v0
	v_mov_b32_e32 v37, v0
	v_mov_b32_e32 v38, v0
	v_mov_b32_e32 v39, v0
	v_mov_b32_e32 v40, v0
	v_mov_b32_e32 v41, v0
	v_mov_b32_e32 v42, v0
	v_mov_b32_e32 v43, v0
	v_mov_b32_e32 v44, v0
	v_mov_b32_e32 v45, v0
	v_mov_b32_e32 v46, v0
	v_mov_b32_e32 v47, v0
	v_mov_b32_e32 v48, v0
	v_mov_b32_e32 v49, v0
	v_mov_b32_e32 v50, v0
	v_mov_b32_e32 v51, v0
	v_mov_b32_e32 v52, v0
	v_mov_b32_e32 v53, v0
	v_mov_b32_e32 v54, v0
	v_mov_b32_e32 v55, v0
	v_mov_b32_e32 v56, v0
	v_mov_b32_e32 v57, v0
	v_mov_b32_e32 v58, v0
	v_mov_b32_e32 v59, v0
	v_mov_b32_e32 v60, v0
	v_mov_b32_e32 v61, v0
	v_mov_b32_e32 v62, v0
	v_mov_b32_e32 v63, v0
	v_mov_b32_e32 v64, v0
	v_mov_b32_e32 v65, v0
	v_mov_b32_e32 v66, v0
	v_mov_b32_e32 v67, v0
	v_mov_b32_e32 v68, v0
	v_mov_b32_e32 v69, v0
	v_mov_b32_e32 v70, v0
	v_mov_b32_e32 v71, v0
	v_mov_b32_e32 v72, v0
	v_mov_b32_e32 v73, v0
	v_mov_b32_e32 v74, v0
	v_mov_b32_e32 v75, v0
	v_mov_b32_e32 v76, v0
	v_mov_b32_e32 v77, v0
	v_mov_b32_e32 v78, v0
	v_mov_b32_e32 v79, v0
	v_mov_b32_e32 v80, v0
	v_mov_b32_e32 v81, v0
	v_mov_b32_e32 v82, v0
	v_mov_b32_e32 v83, v0
	v_mov_b32_e32 v84, v0
	v_mov_b32_e32 v85, v0
	v_mov_b32_e32 v86, v0
	v_mov_b32_e32 v87, v0
	v_mov_b32_e32 v88, v0
	v_mov_b32_e32 v89, v0
	v_mov_b32_e32 v90, v0
	v_mov_b32_e32 v91, v0
	v_mov_b32_e32 v92, v0
	v_mov_b32_e32 v93, v0
	v_mov_b32_e32 v94, v0
	v_mov_b32_e32 v95, v0
	v_mov_b32_e32 v96, v0
	v_mov_b32_e32 v97, v0
	v_mov_b32_e32 v98, v0
	v_mov_b32_e32 v99, v0
	v_mov_b32_e32 v100, v0
	v_mov_b32_e32 v101, v0
	v_mov_b32_e32 v102, v0
	v_mov_b32_e32 v103, v0
	v_mov_b32_e32 v104, v0
	v_mov_b32_e32 v105, v0
	v_mov_b32_e32 v106, v0
	v_mov_b32_e32 v107, v0
	v_mov_b32_e32 v108, v0
	v_mov_b32_e32 v109, v0
	v_mov_b32_e32 v110, v0
	v_mov_b32_e32 v111, v0
	v_mov_b32_e32 v112, v0
	v_mov_b32_e32 v113, v0
	v_mov_b32_e32 v114, v0
	v_mov_b32_e32 v115, v0
	v_mov_b32_e32 v116, v0
	v_mov_b32_e32 v117, v0
	v_mov_b32_e32 v118, v0
	v_mov_b32_e32 v119, v0
	v_mov_b32_e32 v120, v0
	v_mov_b32_e32 v121, v0
	v_mov_b32_e32 v122, v0
	v_mov_b32_e32 v123, v0
	v_mov_b32_e32 v124, v0
	v_mov_b32_e32 v125, v0
	v_mov_b32_e32 v126, v0
	v_mov_b32_e32 v127, v0
	s_mov_b64 s[96:97], 0x19cc0080
	s_mov_b64 vcc, 0x19ce0080
	s_mov_b64 s[14:15], 0x19cc0100
	s_mov_b64 s[16:17], 0x19ce0100
	s_barrier

; #define LDA8(dst, b, h)                                                                                               \
;   _Pragma("unroll") for (int m = 0; m < 4; ++m) _Pragma("unroll") for (int k = 0; k < 2; ++k)                         \
;     dst[m][k] = *(const bf16x8*)(SA8(b, h) + la + m * 2048 + k * 1024)
; #define LDB8(dst, b, h)                                                                                               \
;   _Pragma("unroll") for (int n = 0; n < 2; ++n) _Pragma("unroll") for (int k = 0; k < 2; ++k)                         \
;     dst[n][k] = *(const bf16x8*)(SB8(b, h) + lb + n * 2048 + k * 1024)
; #define WAITV8(n) asm volatile("s_waitcnt vmcnt(" #n ")" ::: "memory")
; #define WAITL8(n) asm volatile("s_waitcnt lgkmcnt(" #n ")" ::: "memory")
; #define BAR8 __builtin_amdgcn_s_barrier()
; #define SCHED8 __builtin_amdgcn_sched_barrier(0)
; template <class Epi>
; DEV void gemm_tile8(char* shm, const u16* __restrict__ A, const u16* __restrict__ Bt, int K, int brow, int bcol, Epi& epi) {
;     ...
;   WAITV8(0);
;   STAGE8(SB8(0, 0), Bt, bcol, 0); STAGE8(SA8(0, 0), A, brow, 0);
;   STAGE8(SB8(0, 1), Bt, bcol + HALF, 0); STAGE8(SA8(0, 1), A, brow + HALF, 0);
;   if (wrs == 1) BAR8;
;   WAITV8(4); BAR8;
;   STAGE8(SB8(1, 0), Bt, bcol, 1); STAGE8(SA8(1, 0), A, brow, 1); STAGE8(SB8(1, 1), Bt, bcol + HALF, 1);
;   WAITV8(6); BAR8;
; #pragma unroll 1
;   for (int t = 0; t < nt - 2; t += 2) {
;     LDB8(B0, 0, 0); SCHED8; LDA8(At, 0, 0); STAGE8(SA8(1, 1), A, brow + HALF, t + 1);
;     WAITL8(8); BAR8; WAITL8(0); MMA8(0, 0, At, B0); BAR8; SCHED8;
;     LDB8(B1, 0, 1); STAGE8(SB8(0, 0), Bt, bcol, t + 2);
;     BAR8; WAITL8(0); MMA8(0, 1, At, B1); BAR8;
;     LDA8(At, 0, 1); STAGE8(SA8(0, 0), A, brow, t + 2);
;     BAR8; WAITL8(0); MMA8(1, 0, At, B0); BAR8; SCHED8;
.LBB0_497:
	s_mov_b64 s[92:93], 0x80
	s_add_i32 s70, s81, 0x18000
	s_waitcnt vmcnt(0)
	v_lshl_add_u64 v[12:13], v[6:7], 0, s[92:93]
	s_mov_b32 m0, s70
	s_mov_b64 s[14:15], 0x8080
	s_add_i32 s54, s81, 0x1a000
	s_waitcnt vmcnt(4)
	s_barrier
	global_load_lds_dwordx4 v[12:13], off
	v_lshl_add_u64 v[12:13], v[6:7], 0, s[14:15]
	s_mov_b32 m0, s54
	s_add_i32 s27, s81, 0x8000
	global_load_lds_dwordx4 v[12:13], off
	v_lshl_add_u64 v[12:13], v[4:5], 0, s[92:93]
	s_mov_b32 m0, s27
	s_add_i32 s25, s81, 0xa000
	global_load_lds_dwordx4 v[12:13], off
	v_lshl_add_u64 v[12:13], v[4:5], 0, s[14:15]
	s_mov_b32 m0, s25
	s_add_i32 s22, s81, 0x1c000
	global_load_lds_dwordx4 v[12:13], off
	v_lshl_add_u64 v[12:13], v[2:3], 0, s[92:93]
	s_mov_b32 m0, s22
	s_add_i32 s23, s81, 0x1e000
	global_load_lds_dwordx4 v[12:13], off
	v_lshl_add_u64 v[12:13], v[2:3], 0, s[14:15]
	s_mov_b32 m0, s23
	v_and_b32_e32 v11, 15, v9
	global_load_lds_dwordx4 v[12:13], off
	v_and_b32_e32 v12, 48, v9
	v_lshlrev_b32_e32 v9, 2, v9
	v_lshlrev_b32_e32 v11, 6, v11
	v_and_b32_e32 v9, 32, v9
	v_or_b32_e32 v13, v11, v12
	v_bitop3_b32 v11, v11, v9, v12 bitop3:0x36
	v_lshlrev_b32_e32 v8, 12, v8
	s_movk_i32 s24, 0x3000
	v_and_or_b32 v203, v8, s24, v11
	v_lshlrev_b32_e32 v10, 13, v10
	v_or_b32_e32 v224, 0x10000, v203
	v_or_b32_e32 v227, 0x10800, v203
	v_bitop3_b32 v140, v13, v10, v9 bitop3:0xde
	s_waitcnt vmcnt(6)
	s_barrier
	v_or_b32_e32 v226, 0x10400, v203
	ds_read_b128 v[10:13], v224
	ds_read_b128 v[14:17], v226
	v_or_b32_e32 v228, 0x10c00, v203
	ds_read_b128 v[18:21], v227
	ds_read_b128 v[22:25], v228
	v_lshl_add_u64 v[58:59], v[0:1], 0, s[92:93]
	v_lshl_add_u64 v[106:107], v[6:7], 0, s[4:5]
	v_lshl_add_u64 v[8:9], v[2:3], 0, s[56:57]
	v_or_b32_e32 v225, 0x14000, v203
	v_or_b32_e32 v244, 0x1c000, v203
	v_lshl_add_u64 v[138:139], v[4:5], 0, s[4:5]
	v_lshl_add_u64 v[190:191], v[0:1], 0, s[4:5]
	v_lshl_add_u64 v[220:221], v[6:7], 0, s[56:57]
	v_lshl_add_u64 v[222:223], v[4:5], 0, s[56:57]
	s_add_i32 s26, s81, 0xc000
	s_mov_b32 m0, s26
	s_add_i32 s24, s81, 0xe000
	ds_read_b128 v[26:29], v140
	ds_read_b128 v[30:33], v140 offset:1024
	ds_read_b128 v[34:37], v140 offset:2048
	ds_read_b128 v[38:41], v140 offset:3072
	ds_read_b128 v[42:45], v140 offset:4096
	ds_read_b128 v[46:49], v140 offset:5120
	ds_read_b128 v[50:53], v140 offset:6144
	ds_read_b128 v[54:57], v140 offset:7168
	global_load_lds_dwordx4 v[58:59], off
	v_lshl_add_u64 v[58:59], v[0:1], 0, s[14:15]
	s_mov_b32 m0, s24
	v_lshl_add_u64 v[166:167], v[2:3], 0, s[4:5]
	global_load_lds_dwordx4 v[58:59], off
	s_waitcnt lgkmcnt(8)
	s_barrier
	s_waitcnt lgkmcnt(0)
	s_setprio 1
	s_waitcnt lgkmcnt(0)
	v_mfma_f32_16x16x32_bf16 v[58:61], v[10:13], v[26:29], 0
	v_or_b32_e32 v232, 0x18000, v203
	v_mfma_f32_16x16x32_bf16 v[62:65], v[18:21], v[26:29], 0
	v_mfma_f32_16x16x32_bf16 v[66:69], v[10:13], v[34:37], 0
	v_mfma_f32_16x16x32_bf16 v[70:73], v[18:21], v[34:37], 0
	v_mfma_f32_16x16x32_bf16 v[74:77], v[10:13], v[42:45], 0
	v_mfma_f32_16x16x32_bf16 v[78:81], v[18:21], v[42:45], 0
	v_mfma_f32_16x16x32_bf16 v[82:85], v[10:13], v[50:53], 0
	v_mfma_f32_16x16x32_bf16 v[86:89], v[18:21], v[50:53], 0
	v_mfma_f32_16x16x32_bf16 v[58:61], v[14:17], v[30:33], v[58:61]
	v_mfma_f32_16x16x32_bf16 v[62:65], v[22:25], v[30:33], v[62:65]
	v_mfma_f32_16x16x32_bf16 v[66:69], v[14:17], v[38:41], v[66:69]
	v_mfma_f32_16x16x32_bf16 v[70:73], v[22:25], v[38:41], v[70:73]
	v_mfma_f32_16x16x32_bf16 v[74:77], v[14:17], v[46:49], v[74:77]
	v_mfma_f32_16x16x32_bf16 v[78:81], v[22:25], v[46:49], v[78:81]
	v_mfma_f32_16x16x32_bf16 v[82:85], v[14:17], v[54:57], v[82:85]
	v_mfma_f32_16x16x32_bf16 v[86:89], v[22:25], v[54:57], v[86:89]
	s_setprio 0
	s_barrier
	s_mov_b32 m0, s90
	v_or_b32_e32 v230, 0x14800, v203
	s_mov_b64 s[14:15], 0x8100
	v_or_b32_e32 v229, 0x14400, v203
	ds_read_b128 v[90:93], v225
	ds_read_b128 v[94:97], v229
	v_or_b32_e32 v231, 0x14c00, v203
	ds_read_b128 v[98:101], v230
	ds_read_b128 v[102:105], v231
	global_load_lds_dwordx4 v[106:107], off
	v_lshl_add_u64 v[106:107], v[6:7], 0, s[14:15]
	s_mov_b32 m0, s85
	s_nop 0
	global_load_lds_dwordx4 v[106:107], off
	s_barrier
	s_waitcnt lgkmcnt(0)
	s_setprio 1
	s_waitcnt lgkmcnt(0)
	v_mfma_f32_16x16x32_bf16 v[106:109], v[90:93], v[26:29], 0
	v_mfma_f32_16x16x32_bf16 v[26:29], v[98:101], v[26:29], 0
	v_mfma_f32_16x16x32_bf16 v[106:109], v[94:97], v[30:33], v[106:109]
	v_mfma_f32_16x16x32_bf16 v[26:29], v[102:105], v[30:33], v[26:29]
	v_mfma_f32_16x16x32_bf16 v[30:33], v[90:93], v[34:37], 0
	v_mfma_f32_16x16x32_bf16 v[34:37], v[98:101], v[34:37], 0
	v_mfma_f32_16x16x32_bf16 v[30:33], v[94:97], v[38:41], v[30:33]
	v_mfma_f32_16x16x32_bf16 v[34:37], v[102:105], v[38:41], v[34:37]
	v_mfma_f32_16x16x32_bf16 v[38:41], v[90:93], v[42:45], 0
	v_mfma_f32_16x16x32_bf16 v[42:45], v[98:101], v[42:45], 0
	v_mfma_f32_16x16x32_bf16 v[38:41], v[94:97], v[46:49], v[38:41]
	v_mfma_f32_16x16x32_bf16 v[42:45], v[102:105], v[46:49], v[42:45]
	v_mfma_f32_16x16x32_bf16 v[46:49], v[90:93], v[50:53], 0
	v_mfma_f32_16x16x32_bf16 v[50:53], v[98:101], v[50:53], 0
	v_mfma_f32_16x16x32_bf16 v[46:49], v[94:97], v[54:57], v[46:49]
	v_mfma_f32_16x16x32_bf16 v[50:53], v[102:105], v[54:57], v[50:53]
	s_setprio 0
	s_mov_b32 m0, s81
	s_barrier
	ds_read_b128 v[54:57], v140 offset:16384
	ds_read_b128 v[110:113], v140 offset:17408
	ds_read_b128 v[114:117], v140 offset:18432
	ds_read_b128 v[118:121], v140 offset:19456
	ds_read_b128 v[122:125], v140 offset:20480
	ds_read_b128 v[126:129], v140 offset:21504
	ds_read_b128 v[130:133], v140 offset:22528
	ds_read_b128 v[134:137], v140 offset:23552
	global_load_lds_dwordx4 v[138:139], off
	v_lshl_add_u64 v[138:139], v[4:5], 0, s[14:15]
	s_mov_b32 m0, s84
	s_nop 0
	global_load_lds_dwordx4 v[138:139], off
	s_barrier
; #define LDA8(dst, b, h)                                                                                               \
;   _Pragma("unroll") for (int m = 0; m < 4; ++m) _Pragma("unroll") for (int k = 0; k < 2; ++k)                         \
;     dst[m][k] = *(const bf16x8*)(SA8(b, h) + la + m * 2048 + k * 1024)
; #define LDB8(dst, b, h)                                                                                               \
;   _Pragma("unroll") for (int n = 0; n < 2; ++n) _Pragma("unroll") for (int k = 0; k < 2; ++k)                         \
;     dst[n][k] = *(const bf16x8*)(SB8(b, h) + lb + n * 2048 + k * 1024)
; #define WAITV8(n) asm volatile("s_waitcnt vmcnt(" #n ")" ::: "memory")
; #define WAITL8(n) asm volatile("s_waitcnt lgkmcnt(" #n ")" ::: "memory")
; #define BAR8 __builtin_amdgcn_s_barrier()
; #define SCHED8 __builtin_amdgcn_sched_barrier(0)
; template <class Epi>
; DEV void gemm_tile8(char* shm, const u16* __restrict__ A, const u16* __restrict__ Bt, int K, int brow, int bcol, Epi& epi) {
;     ...
;     BAR8; WAITL8(0); MMA8(1, 0, At, B0); BAR8; SCHED8;
;     STAGE8(SB8(0, 1), Bt, bcol + HALF, t + 2);
;     WAITV8(6); BAR8; MMA8(1, 1, At, B1); BAR8;
;     LDB8(B0, 1, 0); SCHED8; LDA8(At, 1, 0); STAGE8(SA8(0, 1), A, brow + HALF, t + 2);
;     WAITL8(8); BAR8; WAITL8(0); MMA8(0, 0, At, B0); BAR8; SCHED8;
;     LDB8(B1, 1, 1); STAGE8(SB8(1, 0), Bt, bcol, t + 3);
	s_waitcnt lgkmcnt(0)
	s_setprio 1
	s_waitcnt lgkmcnt(0)
	v_mfma_f32_16x16x32_bf16 v[142:145], v[10:13], v[54:57], 0
	v_mfma_f32_16x16x32_bf16 v[150:153], v[10:13], v[114:117], 0
	v_mfma_f32_16x16x32_bf16 v[158:161], v[10:13], v[122:125], 0
	v_mfma_f32_16x16x32_bf16 v[10:13], v[10:13], v[130:133], 0
	v_mfma_f32_16x16x32_bf16 v[142:145], v[14:17], v[110:113], v[142:145]
	v_mfma_f32_16x16x32_bf16 v[150:153], v[14:17], v[118:121], v[150:153]
	v_mfma_f32_16x16x32_bf16 v[158:161], v[14:17], v[126:129], v[158:161]
	v_mfma_f32_16x16x32_bf16 v[10:13], v[14:17], v[134:137], v[10:13]
	v_mfma_f32_16x16x32_bf16 v[14:17], v[18:21], v[130:133], 0
	v_mfma_f32_16x16x32_bf16 v[146:149], v[18:21], v[54:57], 0
	v_mfma_f32_16x16x32_bf16 v[154:157], v[18:21], v[114:117], 0
	v_mfma_f32_16x16x32_bf16 v[162:165], v[18:21], v[122:125], 0
	v_mfma_f32_16x16x32_bf16 v[14:17], v[22:25], v[134:137], v[14:17]
	v_mfma_f32_16x16x32_bf16 v[146:149], v[22:25], v[110:113], v[146:149]
	v_mfma_f32_16x16x32_bf16 v[154:157], v[22:25], v[118:121], v[154:157]
	v_mfma_f32_16x16x32_bf16 v[162:165], v[22:25], v[126:129], v[162:165]
	s_setprio 0
	s_barrier
	s_mov_b32 m0, s72
	v_lshl_add_u64 v[18:19], v[2:3], 0, s[14:15]
	global_load_lds_dwordx4 v[166:167], off
	s_mov_b32 m0, s73
	s_nop 0
	global_load_lds_dwordx4 v[18:19], off
	s_waitcnt vmcnt(6)
	s_barrier
	s_setprio 1
	v_mfma_f32_16x16x32_bf16 v[18:21], v[90:93], v[54:57], 0
	v_mfma_f32_16x16x32_bf16 v[22:25], v[98:101], v[54:57], 0
	v_mfma_f32_16x16x32_bf16 v[18:21], v[94:97], v[110:113], v[18:21]
	v_mfma_f32_16x16x32_bf16 v[22:25], v[102:105], v[110:113], v[22:25]
	v_mfma_f32_16x16x32_bf16 v[54:57], v[90:93], v[114:117], 0
	v_mfma_f32_16x16x32_bf16 v[110:113], v[98:101], v[114:117], 0
	v_mfma_f32_16x16x32_bf16 v[114:117], v[90:93], v[122:125], 0
	v_mfma_f32_16x16x32_bf16 v[90:93], v[90:93], v[130:133], 0
	v_mfma_f32_16x16x32_bf16 v[54:57], v[94:97], v[118:121], v[54:57]
	v_mfma_f32_16x16x32_bf16 v[110:113], v[102:105], v[118:121], v[110:113]
	v_mfma_f32_16x16x32_bf16 v[114:117], v[94:97], v[126:129], v[114:117]
	v_mfma_f32_16x16x32_bf16 v[118:121], v[98:101], v[122:125], 0
	v_mfma_f32_16x16x32_bf16 v[90:93], v[94:97], v[134:137], v[90:93]
	v_mfma_f32_16x16x32_bf16 v[94:97], v[98:101], v[130:133], 0
	v_mfma_f32_16x16x32_bf16 v[118:121], v[102:105], v[126:129], v[118:121]
	v_mfma_f32_16x16x32_bf16 v[94:97], v[102:105], v[134:137], v[94:97]
	s_setprio 0
	v_or_b32_e32 v234, 0x18800, v203
	s_barrier
	v_or_b32_e32 v233, 0x18400, v203
	ds_read_b128 v[98:101], v232
	ds_read_b128 v[102:105], v233
	v_or_b32_e32 v236, 0x18c00, v203
	ds_read_b128 v[122:125], v234
	ds_read_b128 v[126:129], v236
	s_mov_b32 m0, s71
	ds_read_b128 v[130:133], v140 offset:32768
	ds_read_b128 v[134:137], v140 offset:33792
	ds_read_b128 v[166:169], v140 offset:34816
	ds_read_b128 v[170:173], v140 offset:35840
	ds_read_b128 v[174:177], v140 offset:36864
	ds_read_b128 v[178:181], v140 offset:37888
	ds_read_b128 v[182:185], v140 offset:38912
	ds_read_b128 v[186:189], v140 offset:39936
	global_load_lds_dwordx4 v[190:191], off
	v_lshl_add_u64 v[138:139], v[0:1], 0, s[14:15]
	s_mov_b32 m0, s55
	s_nop 0
	global_load_lds_dwordx4 v[138:139], off
	s_waitcnt lgkmcnt(8)
	s_barrier
	s_waitcnt lgkmcnt(0)
	s_setprio 1
	s_waitcnt lgkmcnt(0)
	v_mfma_f32_16x16x32_bf16 v[58:61], v[98:101], v[130:133], v[58:61]
	v_mfma_f32_16x16x32_bf16 v[62:65], v[122:125], v[130:133], v[62:65]
	v_mfma_f32_16x16x32_bf16 v[66:69], v[98:101], v[166:169], v[66:69]
	v_mfma_f32_16x16x32_bf16 v[70:73], v[122:125], v[166:169], v[70:73]
	v_mfma_f32_16x16x32_bf16 v[74:77], v[98:101], v[174:177], v[74:77]
	v_mfma_f32_16x16x32_bf16 v[78:81], v[122:125], v[174:177], v[78:81]
	v_mfma_f32_16x16x32_bf16 v[82:85], v[98:101], v[182:185], v[82:85]
	v_mfma_f32_16x16x32_bf16 v[86:89], v[122:125], v[182:185], v[86:89]
	v_mfma_f32_16x16x32_bf16 v[58:61], v[102:105], v[134:137], v[58:61]
	v_mfma_f32_16x16x32_bf16 v[62:65], v[126:129], v[134:137], v[62:65]
	v_mfma_f32_16x16x32_bf16 v[66:69], v[102:105], v[170:173], v[66:69]
	v_mfma_f32_16x16x32_bf16 v[70:73], v[126:129], v[170:173], v[70:73]
	v_mfma_f32_16x16x32_bf16 v[74:77], v[102:105], v[178:181], v[74:77]
	v_mfma_f32_16x16x32_bf16 v[78:81], v[126:129], v[178:181], v[78:81]
	v_mfma_f32_16x16x32_bf16 v[82:85], v[102:105], v[186:189], v[82:85]
	v_mfma_f32_16x16x32_bf16 v[86:89], v[126:129], v[186:189], v[86:89]
	s_setprio 0
	s_barrier
	s_mov_b32 m0, s70
	v_or_b32_e32 v191, 0x1c800, v203
	s_mov_b64 s[14:15], 0x8180
	v_or_b32_e32 v190, 0x1c400, v203
	ds_read_b128 v[204:207], v244
	ds_read_b128 v[208:211], v190
	v_or_b32_e32 v203, 0x1cc00, v203
	ds_read_b128 v[212:215], v191
	ds_read_b128 v[216:219], v203
	global_load_lds_dwordx4 v[220:221], off
	v_lshl_add_u64 v[6:7], v[6:7], 0, s[14:15]
	s_mov_b32 m0, s54
	s_nop 0
	global_load_lds_dwordx4 v[6:7], off
	s_barrier
	s_waitcnt lgkmcnt(0)
	s_setprio 1
	s_waitcnt lgkmcnt(0)
	v_mfma_f32_16x16x32_bf16 v[106:109], v[204:207], v[130:133], v[106:109]
	v_mfma_f32_16x16x32_bf16 v[26:29], v[212:215], v[130:133], v[26:29]
	v_mfma_f32_16x16x32_bf16 v[30:33], v[204:207], v[166:169], v[30:33]
	v_mfma_f32_16x16x32_bf16 v[34:37], v[212:215], v[166:169], v[34:37]
	v_mfma_f32_16x16x32_bf16 v[38:41], v[204:207], v[174:177], v[38:41]
	v_mfma_f32_16x16x32_bf16 v[42:45], v[212:215], v[174:177], v[42:45]
	v_mfma_f32_16x16x32_bf16 v[46:49], v[204:207], v[182:185], v[46:49]
	v_mfma_f32_16x16x32_bf16 v[50:53], v[212:215], v[182:185], v[50:53]
	v_mfma_f32_16x16x32_bf16 v[106:109], v[208:211], v[134:137], v[106:109]
	v_mfma_f32_16x16x32_bf16 v[26:29], v[216:219], v[134:137], v[26:29]
	v_mfma_f32_16x16x32_bf16 v[30:33], v[208:211], v[170:173], v[30:33]
	v_mfma_f32_16x16x32_bf16 v[34:37], v[216:219], v[170:173], v[34:37]
	v_mfma_f32_16x16x32_bf16 v[38:41], v[208:211], v[178:181], v[38:41]
	v_mfma_f32_16x16x32_bf16 v[42:45], v[216:219], v[178:181], v[42:45]
	v_mfma_f32_16x16x32_bf16 v[46:49], v[208:211], v[186:189], v[46:49]
	v_mfma_f32_16x16x32_bf16 v[50:53], v[216:219], v[186:189], v[50:53]
	s_setprio 0
	s_mov_b32 m0, s27
	s_barrier
; #define LDA8(dst, b, h)                                                                                               \
;   _Pragma("unroll") for (int m = 0; m < 4; ++m) _Pragma("unroll") for (int k = 0; k < 2; ++k)                         \
;     dst[m][k] = *(const bf16x8*)(SA8(b, h) + la + m * 2048 + k * 1024)
; #define LDB8(dst, b, h)                                                                                               \
;   _Pragma("unroll") for (int n = 0; n < 2; ++n) _Pragma("unroll") for (int k = 0; k < 2; ++k)                         \
;     dst[n][k] = *(const bf16x8*)(SB8(b, h) + lb + n * 2048 + k * 1024)
; #define WAITV8(n) asm volatile("s_waitcnt vmcnt(" #n ")" ::: "memory")
; #define WAITL8(n) asm volatile("s_waitcnt lgkmcnt(" #n ")" ::: "memory")
; #define BAR8 __builtin_amdgcn_s_barrier()
; #define SCHED8 __builtin_amdgcn_sched_barrier(0)
; template <class Epi>
; DEV void gemm_tile8(char* shm, const u16* __restrict__ A, const u16* __restrict__ Bt, int K, int brow, int bcol, Epi& epi) {
;     ...
;     BAR8; WAITL8(0); MMA8(0, 1, At, B1); BAR8;
;     LDA8(At, 1, 1); STAGE8(SA8(1, 0), A, brow, t + 3);
;     BAR8; WAITL8(0); MMA8(1, 0, At, B0); BAR8; SCHED8;
;     STAGE8(SB8(1, 1), Bt, bcol + HALF, t + 3);
;     WAITV8(6); BAR8; MMA8(1, 1, At, B1); BAR8;
;   }
;   { LDB8(B0, 0, 0); LDA8(At, 0, 0); STAGE8(SA8(1, 1), A, brow + HALF, nt - 1);
;     BAR8; WAITL8(0); MMA8(0, 0, At, B0); BAR8;
;     LDB8(B1, 0, 1); BAR8; WAITL8(0); MMA8(0, 1, At, B1); BAR8;
	ds_read_b128 v[130:133], v140 offset:49152
	ds_read_b128 v[134:137], v140 offset:50176
	ds_read_b128 v[166:169], v140 offset:51200
	ds_read_b128 v[170:173], v140 offset:52224
	ds_read_b128 v[174:177], v140 offset:53248
	ds_read_b128 v[178:181], v140 offset:54272
	ds_read_b128 v[182:185], v140 offset:55296
	ds_read_b128 v[186:189], v140 offset:56320
	global_load_lds_dwordx4 v[222:223], off
	v_lshl_add_u64 v[4:5], v[4:5], 0, s[14:15]
	s_mov_b32 m0, s25
	s_nop 0
	global_load_lds_dwordx4 v[4:5], off
	s_barrier
	s_waitcnt lgkmcnt(0)
	s_setprio 1
	s_waitcnt lgkmcnt(0)
	v_mfma_f32_16x16x32_bf16 v[4:7], v[98:101], v[130:133], v[142:145]
	v_mfma_f32_16x16x32_bf16 v[10:13], v[98:101], v[182:185], v[10:13]
	v_mfma_f32_16x16x32_bf16 v[14:17], v[122:125], v[182:185], v[14:17]
	v_mfma_f32_16x16x32_bf16 v[4:7], v[102:105], v[134:137], v[4:7]
	v_mfma_f32_16x16x32_bf16 v[142:145], v[122:125], v[130:133], v[146:149]
	v_mfma_f32_16x16x32_bf16 v[146:149], v[98:101], v[166:169], v[150:153]
	v_mfma_f32_16x16x32_bf16 v[150:153], v[122:125], v[166:169], v[154:157]
	v_mfma_f32_16x16x32_bf16 v[154:157], v[98:101], v[174:177], v[158:161]
	v_mfma_f32_16x16x32_bf16 v[158:161], v[122:125], v[174:177], v[162:165]
	v_mfma_f32_16x16x32_bf16 v[10:13], v[102:105], v[186:189], v[10:13]
	v_mfma_f32_16x16x32_bf16 v[14:17], v[126:129], v[186:189], v[14:17]
	v_mfma_f32_16x16x32_bf16 v[142:145], v[126:129], v[134:137], v[142:145]
	v_mfma_f32_16x16x32_bf16 v[146:149], v[102:105], v[170:173], v[146:149]
	v_mfma_f32_16x16x32_bf16 v[150:153], v[126:129], v[170:173], v[150:153]
	v_mfma_f32_16x16x32_bf16 v[154:157], v[102:105], v[178:181], v[154:157]
	v_mfma_f32_16x16x32_bf16 v[158:161], v[126:129], v[178:181], v[158:161]
	s_setprio 0
	s_barrier
	s_mov_b32 m0, s22
	v_lshl_add_u64 v[2:3], v[2:3], 0, s[14:15]
	global_load_lds_dwordx4 v[8:9], off
	s_mov_b32 m0, s23
	s_nop 0
	global_load_lds_dwordx4 v[2:3], off
	s_waitcnt vmcnt(6)
	s_barrier
	s_setprio 1
	v_mfma_f32_16x16x32_bf16 v[18:21], v[204:207], v[130:133], v[18:21]
	v_mfma_f32_16x16x32_bf16 v[22:25], v[212:215], v[130:133], v[22:25]
	v_mfma_f32_16x16x32_bf16 v[54:57], v[204:207], v[166:169], v[54:57]
	v_mfma_f32_16x16x32_bf16 v[98:101], v[212:215], v[166:169], v[110:113]
	v_mfma_f32_16x16x32_bf16 v[102:105], v[204:207], v[174:177], v[114:117]
	v_mfma_f32_16x16x32_bf16 v[110:113], v[212:215], v[174:177], v[118:121]
	v_mfma_f32_16x16x32_bf16 v[90:93], v[204:207], v[182:185], v[90:93]
	v_mfma_f32_16x16x32_bf16 v[94:97], v[212:215], v[182:185], v[94:97]
	v_mfma_f32_16x16x32_bf16 v[18:21], v[208:211], v[134:137], v[18:21]
	v_mfma_f32_16x16x32_bf16 v[22:25], v[216:219], v[134:137], v[22:25]
	v_mfma_f32_16x16x32_bf16 v[54:57], v[208:211], v[170:173], v[54:57]
	v_mfma_f32_16x16x32_bf16 v[98:101], v[216:219], v[170:173], v[98:101]
	v_mfma_f32_16x16x32_bf16 v[102:105], v[208:211], v[178:181], v[102:105]
	v_mfma_f32_16x16x32_bf16 v[110:113], v[216:219], v[178:181], v[110:113]
	v_mfma_f32_16x16x32_bf16 v[90:93], v[208:211], v[186:189], v[90:93]
	v_mfma_f32_16x16x32_bf16 v[94:97], v[216:219], v[186:189], v[94:97]
	s_setprio 0
	s_mov_b32 m0, s26
	v_lshl_add_u64 v[2:3], v[0:1], 0, s[56:57]
	s_barrier
	ds_read_b128 v[114:117], v224
	ds_read_b128 v[118:121], v226
	ds_read_b128 v[122:125], v227
	ds_read_b128 v[126:129], v228
	ds_read_b128 v[130:133], v140
	ds_read_b128 v[134:137], v140 offset:1024
	ds_read_b128 v[162:165], v140 offset:2048
	ds_read_b128 v[166:169], v140 offset:3072
	ds_read_b128 v[170:173], v140 offset:4096
	ds_read_b128 v[174:177], v140 offset:5120
	ds_read_b128 v[178:181], v140 offset:6144
	ds_read_b128 v[182:185], v140 offset:7168
	global_load_lds_dwordx4 v[2:3], off
	v_lshl_add_u64 v[0:1], v[0:1], 0, s[14:15]
	s_mov_b32 m0, s24
	s_nop 0
	global_load_lds_dwordx4 v[0:1], off
	s_barrier
	s_waitcnt lgkmcnt(0)
	s_setprio 1
	s_waitcnt lgkmcnt(0)
	v_mfma_f32_16x16x32_bf16 v[0:3], v[114:117], v[130:133], v[58:61]
	v_mfma_f32_16x16x32_bf16 v[58:61], v[122:125], v[130:133], v[62:65]
	v_mfma_f32_16x16x32_bf16 v[62:65], v[114:117], v[162:165], v[66:69]
	v_mfma_f32_16x16x32_bf16 v[186:189], v[118:121], v[166:169], v[62:65]
	v_mfma_f32_16x16x32_bf16 v[62:65], v[122:125], v[162:165], v[70:73]
	v_mfma_f32_16x16x32_bf16 v[204:207], v[126:129], v[166:169], v[62:65]
	v_mfma_f32_16x16x32_bf16 v[62:65], v[114:117], v[170:173], v[74:77]
	v_mfma_f32_16x16x32_bf16 v[208:211], v[118:121], v[174:177], v[62:65]
	v_mfma_f32_16x16x32_bf16 v[62:65], v[122:125], v[170:173], v[78:81]
	v_mfma_f32_16x16x32_bf16 v[212:215], v[126:129], v[174:177], v[62:65]
	v_mfma_f32_16x16x32_bf16 v[62:65], v[114:117], v[178:181], v[82:85]
	v_mfma_f32_16x16x32_bf16 v[0:3], v[118:121], v[134:137], v[0:3]
	v_mfma_f32_16x16x32_bf16 v[58:61], v[126:129], v[134:137], v[58:61]
	v_mfma_f32_16x16x32_bf16 v[216:219], v[118:121], v[182:185], v[62:65]
	v_mfma_f32_16x16x32_bf16 v[62:65], v[122:125], v[178:181], v[86:89]
	v_mfma_f32_16x16x32_bf16 v[220:223], v[126:129], v[182:185], v[62:65]
	s_setprio 0
	s_barrier
	s_nop 3
	ds_read_b128 v[62:65], v225
	ds_read_b128 v[66:69], v229
	ds_read_b128 v[70:73], v230
	ds_read_b128 v[74:77], v231
	s_barrier
; #define LDA8(dst, b, h)                                                                                               \
;   _Pragma("unroll") for (int m = 0; m < 4; ++m) _Pragma("unroll") for (int k = 0; k < 2; ++k)                         \
;     dst[m][k] = *(const bf16x8*)(SA8(b, h) + la + m * 2048 + k * 1024)
; #define LDB8(dst, b, h)                                                                                               \
;   _Pragma("unroll") for (int n = 0; n < 2; ++n) _Pragma("unroll") for (int k = 0; k < 2; ++k)                         \
;     dst[n][k] = *(const bf16x8*)(SB8(b, h) + lb + n * 2048 + k * 1024)
; #define WAITV8(n) asm volatile("s_waitcnt vmcnt(" #n ")" ::: "memory")
; #define WAITL8(n) asm volatile("s_waitcnt lgkmcnt(" #n ")" ::: "memory")
; #define BAR8 __builtin_amdgcn_s_barrier()
; template <class Epi>
; DEV void gemm_tile8(char* shm, const u16* __restrict__ A, const u16* __restrict__ Bt, int K, int brow, int bcol, Epi& epi) {
;     ...
;     LDB8(B1, 0, 1); BAR8; WAITL8(0); MMA8(0, 1, At, B1); BAR8;
;     LDA8(At, 0, 1); WAITV8(4); BAR8; WAITL8(0); MMA8(1, 0, At, B0); MMA8(1, 1, At, B1); BAR8; }
;   { LDB8(B0, 1, 0); LDA8(At, 1, 0); WAITV8(2); BAR8; WAITL8(0); MMA8(0, 0, At, B0); BAR8;
	s_waitcnt lgkmcnt(0)
	s_setprio 1
	s_waitcnt lgkmcnt(3)
	v_mfma_f32_16x16x32_bf16 v[78:81], v[62:65], v[130:133], v[106:109]
	s_waitcnt lgkmcnt(1)
	v_mfma_f32_16x16x32_bf16 v[26:29], v[70:73], v[130:133], v[26:29]
	v_mfma_f32_16x16x32_bf16 v[30:33], v[62:65], v[162:165], v[30:33]
	v_mfma_f32_16x16x32_bf16 v[34:37], v[70:73], v[162:165], v[34:37]
	v_mfma_f32_16x16x32_bf16 v[38:41], v[62:65], v[170:173], v[38:41]
	v_mfma_f32_16x16x32_bf16 v[42:45], v[70:73], v[170:173], v[42:45]
	v_mfma_f32_16x16x32_bf16 v[46:49], v[62:65], v[178:181], v[46:49]
	v_mfma_f32_16x16x32_bf16 v[50:53], v[70:73], v[178:181], v[50:53]
	v_mfma_f32_16x16x32_bf16 v[106:109], v[66:69], v[134:137], v[78:81]
	s_waitcnt lgkmcnt(0)
	v_mfma_f32_16x16x32_bf16 v[26:29], v[74:77], v[134:137], v[26:29]
	v_mfma_f32_16x16x32_bf16 v[30:33], v[66:69], v[166:169], v[30:33]
	v_mfma_f32_16x16x32_bf16 v[34:37], v[74:77], v[166:169], v[34:37]
	v_mfma_f32_16x16x32_bf16 v[38:41], v[66:69], v[174:177], v[38:41]
	v_mfma_f32_16x16x32_bf16 v[42:45], v[74:77], v[174:177], v[42:45]
	v_mfma_f32_16x16x32_bf16 v[46:49], v[66:69], v[182:185], v[46:49]
	v_mfma_f32_16x16x32_bf16 v[50:53], v[74:77], v[182:185], v[50:53]
	s_setprio 0
	s_barrier
	ds_read_b128 v[78:81], v140 offset:16384
	ds_read_b128 v[82:85], v140 offset:17408
	ds_read_b128 v[86:89], v140 offset:18432
	ds_read_b128 v[130:133], v140 offset:19456
	ds_read_b128 v[134:137], v140 offset:20480
	ds_read_b128 v[162:165], v140 offset:21504
	ds_read_b128 v[166:169], v140 offset:22528
	ds_read_b128 v[170:173], v140 offset:23552
	s_waitcnt vmcnt(4)
	s_barrier
	s_waitcnt lgkmcnt(0)
	s_setprio 1
	s_waitcnt lgkmcnt(7)
	v_mfma_f32_16x16x32_bf16 v[4:7], v[114:117], v[78:81], v[4:7]
	s_waitcnt lgkmcnt(1)
	v_mfma_f32_16x16x32_bf16 v[8:11], v[114:117], v[166:169], v[10:13]
	v_mfma_f32_16x16x32_bf16 v[4:7], v[118:121], v[82:85], v[4:7]
	v_mfma_f32_16x16x32_bf16 v[142:145], v[122:125], v[78:81], v[142:145]
	v_mfma_f32_16x16x32_bf16 v[146:149], v[114:117], v[86:89], v[146:149]
	v_mfma_f32_16x16x32_bf16 v[150:153], v[122:125], v[86:89], v[150:153]
	v_mfma_f32_16x16x32_bf16 v[154:157], v[114:117], v[134:137], v[154:157]
	v_mfma_f32_16x16x32_bf16 v[158:161], v[122:125], v[134:137], v[158:161]
	s_waitcnt lgkmcnt(0)
	v_mfma_f32_16x16x32_bf16 v[174:177], v[118:121], v[170:173], v[8:11]
	v_mfma_f32_16x16x32_bf16 v[8:11], v[122:125], v[166:169], v[14:17]
	v_mfma_f32_16x16x32_bf16 v[142:145], v[126:129], v[82:85], v[142:145]
	v_mfma_f32_16x16x32_bf16 v[146:149], v[118:121], v[130:133], v[146:149]
	v_mfma_f32_16x16x32_bf16 v[150:153], v[126:129], v[130:133], v[150:153]
	v_mfma_f32_16x16x32_bf16 v[154:157], v[118:121], v[162:165], v[154:157]
	v_mfma_f32_16x16x32_bf16 v[158:161], v[126:129], v[162:165], v[158:161]
	v_mfma_f32_16x16x32_bf16 v[178:181], v[126:129], v[170:173], v[8:11]
	s_setprio 0
	s_setprio 1
	v_mfma_f32_16x16x32_bf16 v[8:11], v[62:65], v[78:81], v[18:21]
	v_mfma_f32_16x16x32_bf16 v[182:185], v[66:69], v[82:85], v[8:11]
	v_mfma_f32_16x16x32_bf16 v[8:11], v[70:73], v[78:81], v[22:25]
	v_mfma_f32_16x16x32_bf16 v[224:227], v[74:77], v[82:85], v[8:11]
	v_mfma_f32_16x16x32_bf16 v[8:11], v[62:65], v[86:89], v[54:57]
	v_mfma_f32_16x16x32_bf16 v[54:57], v[66:69], v[130:133], v[8:11]
	v_mfma_f32_16x16x32_bf16 v[8:11], v[70:73], v[86:89], v[98:101]
	v_mfma_f32_16x16x32_bf16 v[128:131], v[74:77], v[130:133], v[8:11]
	v_mfma_f32_16x16x32_bf16 v[8:11], v[62:65], v[134:137], v[102:105]
	v_mfma_f32_16x16x32_bf16 v[228:231], v[66:69], v[162:165], v[8:11]
	v_mfma_f32_16x16x32_bf16 v[8:11], v[70:73], v[134:137], v[110:113]
	v_mfma_f32_16x16x32_bf16 v[132:135], v[74:77], v[162:165], v[8:11]
	v_mfma_f32_16x16x32_bf16 v[8:11], v[62:65], v[166:169], v[90:93]
	v_mfma_f32_16x16x32_bf16 v[136:139], v[66:69], v[170:173], v[8:11]
	v_mfma_f32_16x16x32_bf16 v[8:11], v[70:73], v[166:169], v[94:97]
	v_mfma_f32_16x16x32_bf16 v[162:165], v[74:77], v[170:173], v[8:11]
	s_setprio 0
	s_barrier
	ds_read_b128 v[166:169], v232
	ds_read_b128 v[170:173], v233
	ds_read_b128 v[232:235], v234
	ds_read_b128 v[236:239], v236
	s_nop 0
	ds_read_b128 v[8:11], v140 offset:32768
	ds_read_b128 v[12:15], v140 offset:33792
	ds_read_b128 v[16:19], v140 offset:34816
	ds_read_b128 v[20:23], v140 offset:35840
	ds_read_b128 v[116:119], v140 offset:36864
	ds_read_b128 v[120:123], v140 offset:37888
	ds_read_b128 v[124:127], v140 offset:38912
	ds_read_b128 v[240:243], v140 offset:39936
	s_waitcnt vmcnt(2)
	s_barrier
; #define LDA8(dst, b, h)                                                                                               \
;   _Pragma("unroll") for (int m = 0; m < 4; ++m) _Pragma("unroll") for (int k = 0; k < 2; ++k)                         \
;     dst[m][k] = *(const bf16x8*)(SA8(b, h) + la + m * 2048 + k * 1024)
; #define LDB8(dst, b, h)                                                                                               \
;   _Pragma("unroll") for (int n = 0; n < 2; ++n) _Pragma("unroll") for (int k = 0; k < 2; ++k)                         \
;     dst[n][k] = *(const bf16x8*)(SB8(b, h) + lb + n * 2048 + k * 1024)
; #define WAITV8(n) asm volatile("s_waitcnt vmcnt(" #n ")" ::: "memory")
; #define WAITL8(n) asm volatile("s_waitcnt lgkmcnt(" #n ")" ::: "memory")
; #define BAR8 __builtin_amdgcn_s_barrier()
; template <class Epi>
; DEV void gemm_tile8(char* shm, const u16* __restrict__ A, const u16* __restrict__ Bt, int K, int brow, int bcol, Epi& epi) {
;     ...
;   { LDB8(B0, 1, 0); LDA8(At, 1, 0); WAITV8(2); BAR8; WAITL8(0); MMA8(0, 0, At, B0); BAR8;
;     LDB8(B1, 1, 1); WAITV8(0); BAR8; WAITL8(0); MMA8(0, 1, At, B1); BAR8;
;     LDA8(At, 1, 1); BAR8; WAITL8(0); MMA8(1, 0, At, B0); MMA8(1, 1, At, B1); BAR8; }
;   if (wrs == 0) BAR8;
	s_waitcnt lgkmcnt(0)
	s_setprio 1
	s_waitcnt lgkmcnt(7)
	v_mfma_f32_16x16x32_bf16 v[0:3], v[166:169], v[8:11], v[0:3]
	s_waitcnt lgkmcnt(6)
	v_mfma_f32_16x16x32_bf16 v[72:75], v[170:173], v[12:15], v[0:3]
	v_mfma_f32_16x16x32_bf16 v[0:3], v[232:235], v[8:11], v[58:61]
	v_mfma_f32_16x16x32_bf16 v[64:67], v[236:239], v[12:15], v[0:3]
	s_waitcnt lgkmcnt(5)
	v_mfma_f32_16x16x32_bf16 v[0:3], v[166:169], v[16:19], v[186:189]
	s_waitcnt lgkmcnt(4)
	v_mfma_f32_16x16x32_bf16 v[68:71], v[170:173], v[20:23], v[0:3]
	v_mfma_f32_16x16x32_bf16 v[0:3], v[232:235], v[16:19], v[204:207]
	v_mfma_f32_16x16x32_bf16 v[76:79], v[236:239], v[20:23], v[0:3]
	s_waitcnt lgkmcnt(3)
	v_mfma_f32_16x16x32_bf16 v[0:3], v[166:169], v[116:119], v[208:211]
	s_waitcnt lgkmcnt(2)
	v_mfma_f32_16x16x32_bf16 v[80:83], v[170:173], v[120:123], v[0:3]
	v_mfma_f32_16x16x32_bf16 v[0:3], v[232:235], v[116:119], v[212:215]
	v_mfma_f32_16x16x32_bf16 v[84:87], v[236:239], v[120:123], v[0:3]
	s_waitcnt lgkmcnt(1)
	v_mfma_f32_16x16x32_bf16 v[0:3], v[166:169], v[124:127], v[216:219]
	s_waitcnt lgkmcnt(0)
	v_mfma_f32_16x16x32_bf16 v[88:91], v[170:173], v[240:243], v[0:3]
	v_mfma_f32_16x16x32_bf16 v[0:3], v[232:235], v[124:127], v[220:223]
	v_mfma_f32_16x16x32_bf16 v[92:95], v[236:239], v[240:243], v[0:3]
	s_setprio 0
	s_barrier
	ds_read_b128 v[58:61], v244
	ds_read_b128 v[186:189], v190
	ds_read_b128 v[204:207], v191
	ds_read_b128 v[208:211], v203
	s_waitcnt vmcnt(0)
	s_barrier
	s_waitcnt lgkmcnt(0)
	s_setprio 1
	s_waitcnt lgkmcnt(3)
	v_mfma_f32_16x16x32_bf16 v[0:3], v[58:61], v[8:11], v[106:109]
	s_waitcnt lgkmcnt(2)
	v_mfma_f32_16x16x32_bf16 v[104:107], v[186:189], v[12:15], v[0:3]
	s_waitcnt lgkmcnt(1)
	v_mfma_f32_16x16x32_bf16 v[0:3], v[204:207], v[8:11], v[26:29]
	s_waitcnt lgkmcnt(0)
	v_mfma_f32_16x16x32_bf16 v[96:99], v[208:211], v[12:15], v[0:3]
	v_mfma_f32_16x16x32_bf16 v[0:3], v[58:61], v[16:19], v[30:33]
	v_mfma_f32_16x16x32_bf16 v[100:103], v[186:189], v[20:23], v[0:3]
	v_mfma_f32_16x16x32_bf16 v[0:3], v[204:207], v[16:19], v[34:37]
	v_mfma_f32_16x16x32_bf16 v[108:111], v[208:211], v[20:23], v[0:3]
	v_mfma_f32_16x16x32_bf16 v[0:3], v[58:61], v[116:119], v[38:41]
	v_mfma_f32_16x16x32_bf16 v[112:115], v[186:189], v[120:123], v[0:3]
	v_mfma_f32_16x16x32_bf16 v[0:3], v[204:207], v[116:119], v[42:45]
	v_mfma_f32_16x16x32_bf16 v[116:119], v[208:211], v[120:123], v[0:3]
	v_mfma_f32_16x16x32_bf16 v[0:3], v[58:61], v[124:127], v[46:49]
	v_mfma_f32_16x16x32_bf16 v[120:123], v[186:189], v[240:243], v[0:3]
	v_mfma_f32_16x16x32_bf16 v[0:3], v[204:207], v[124:127], v[50:53]
	v_mfma_f32_16x16x32_bf16 v[124:127], v[208:211], v[240:243], v[0:3]
	s_setprio 0
	s_barrier
	ds_read_b128 v[36:39], v140 offset:49152
	ds_read_b128 v[40:43], v140 offset:50176
	ds_read_b128 v[44:47], v140 offset:51200
	ds_read_b128 v[48:51], v140 offset:52224
	ds_read_b128 v[212:215], v140 offset:53248
	ds_read_b128 v[216:219], v140 offset:54272
	ds_read_b128 v[220:223], v140 offset:55296
	ds_read_b128 v[240:243], v140 offset:56320
	s_barrier
	s_waitcnt lgkmcnt(0)
	s_setprio 1
	s_waitcnt lgkmcnt(7)
	v_mfma_f32_16x16x32_bf16 v[0:3], v[166:169], v[36:39], v[4:7]
	v_mfma_f32_16x16x32_bf16 v[4:7], v[232:235], v[36:39], v[142:145]
	s_waitcnt lgkmcnt(5)
	v_mfma_f32_16x16x32_bf16 v[8:11], v[166:169], v[44:47], v[146:149]
	v_mfma_f32_16x16x32_bf16 v[12:15], v[232:235], v[44:47], v[150:153]
	s_waitcnt lgkmcnt(3)
	v_mfma_f32_16x16x32_bf16 v[16:19], v[166:169], v[212:215], v[154:157]
	v_mfma_f32_16x16x32_bf16 v[20:23], v[232:235], v[212:215], v[158:161]
	s_waitcnt lgkmcnt(1)
	v_mfma_f32_16x16x32_bf16 v[24:27], v[166:169], v[220:223], v[174:177]
	v_mfma_f32_16x16x32_bf16 v[28:31], v[232:235], v[220:223], v[178:181]
	v_mfma_f32_16x16x32_bf16 v[0:3], v[170:173], v[40:43], v[0:3]
	v_mfma_f32_16x16x32_bf16 v[4:7], v[236:239], v[40:43], v[4:7]
	v_mfma_f32_16x16x32_bf16 v[8:11], v[170:173], v[48:51], v[8:11]
	v_mfma_f32_16x16x32_bf16 v[12:15], v[236:239], v[48:51], v[12:15]
	v_mfma_f32_16x16x32_bf16 v[16:19], v[170:173], v[216:219], v[16:19]
	v_mfma_f32_16x16x32_bf16 v[20:23], v[236:239], v[216:219], v[20:23]
	s_waitcnt lgkmcnt(0)
	v_mfma_f32_16x16x32_bf16 v[24:27], v[170:173], v[240:243], v[24:27]
	v_mfma_f32_16x16x32_bf16 v[28:31], v[236:239], v[240:243], v[28:31]
	s_setprio 0
	s_setprio 1
	v_mfma_f32_16x16x32_bf16 v[32:35], v[58:61], v[36:39], v[182:185]
	v_mfma_f32_16x16x32_bf16 v[36:39], v[204:207], v[36:39], v[224:227]
	v_mfma_f32_16x16x32_bf16 v[32:35], v[186:189], v[40:43], v[32:35]
	v_mfma_f32_16x16x32_bf16 v[36:39], v[208:211], v[40:43], v[36:39]
	v_mfma_f32_16x16x32_bf16 v[40:43], v[58:61], v[44:47], v[54:57]
	v_mfma_f32_16x16x32_bf16 v[44:47], v[204:207], v[44:47], v[128:131]
	v_mfma_f32_16x16x32_bf16 v[40:43], v[186:189], v[48:51], v[40:43]
	v_mfma_f32_16x16x32_bf16 v[44:47], v[208:211], v[48:51], v[44:47]
	v_mfma_f32_16x16x32_bf16 v[48:51], v[58:61], v[212:215], v[228:231]
	v_mfma_f32_16x16x32_bf16 v[52:55], v[204:207], v[212:215], v[132:135]
	v_mfma_f32_16x16x32_bf16 v[56:59], v[58:61], v[220:223], v[136:139]
	v_mfma_f32_16x16x32_bf16 v[60:63], v[204:207], v[220:223], v[162:165]
	v_mfma_f32_16x16x32_bf16 v[48:51], v[186:189], v[216:219], v[48:51]
	v_mfma_f32_16x16x32_bf16 v[52:55], v[208:211], v[216:219], v[52:55]
	v_mfma_f32_16x16x32_bf16 v[56:59], v[186:189], v[240:243], v[56:59]
	v_mfma_f32_16x16x32_bf16 v[60:63], v[208:211], v[240:243], v[60:63]
	s_setprio 0
	s_cmp_lg_u32 s21, 0
	s_barrier
	s_cbranch_scc1 .LBB0_499
	s_barrier

; #define WAITV8(n) asm volatile("s_waitcnt vmcnt(" #n ")" ::: "memory")
; #define BAR8 __builtin_amdgcn_s_barrier()
;   DEV void tile_begin(int brow, char* shm, int tid) const { rstd_tile_begin(ss, brow, shm, tid); }
;   DEV void tile_begin(int brow, char* shm, int tid) const { rstd_tile_begin(ss, brow, shm, tid); }
; template <class Epi>
; DEV void gemm_tile8(char* shm, const u16* __restrict__ A, const u16* __restrict__ Bt, int K, int brow, int bcol, Epi& epi) {
;     ...
;   { int r_, c_; stage_rc<2>(wid * 1024 + lane * 16, r_, c_); so0 = r_ * K + c_; }
;   const int wids = __builtin_amdgcn_readfirstlane(wid);
;   const int la = lds_byte<2>(wr * 64 + fr, fq * 8), lb = lds_byte<2>(wc * 32 + fr, fq * 8);
;   f32x4 acc[2][2][4][2];
; #pragma unroll
;   for (int a = 0; a < 2; ++a)
; #pragma unroll
;     for (int b = 0; b < 2; ++b)
; #pragma unroll
;       for (int m = 0; m < 4; ++m)
; #pragma unroll
;         for (int n = 0; n < 2; ++n) acc[a][b][m][n] = f32x4{0.f, 0.f, 0.f, 0.f};
;   bf16x8 At[4][2], B0[2][2], B1[2][2];
;   const int nt = K / BK;
;   epi.tile_begin(brow, shm, tid);
;     ...
;   WAITV8(0);
;   STAGE8(SB8(0, 0), Bt, bcol, 0); STAGE8(SA8(0, 0), A, brow, 0);
;   STAGE8(SB8(0, 1), Bt, bcol + HALF, 0); STAGE8(SA8(0, 1), A, brow + HALF, 0);
;   if (wrs == 1) BAR8;
;   WAITV8(4); BAR8;
;   STAGE8(SB8(1, 0), Bt, bcol, 1); STAGE8(SA8(1, 0), A, brow, 1); STAGE8(SB8(1, 1), Bt, bcol + HALF, 1);
;   WAITV8(6); BAR8;
.LBB0_527:
	v_and_b32_e32 v12, 15, v10
	v_and_b32_e32 v13, 48, v10
	v_lshlrev_b32_e32 v10, 2, v10
	v_lshlrev_b32_e32 v12, 6, v12
	v_and_b32_e32 v10, 32, v10
	v_or_b32_e32 v14, v12, v13
	v_bitop3_b32 v12, v12, v10, v13 bitop3:0x36
	v_lshlrev_b32_e32 v13, 12, v6
	s_movk_i32 s20, 0x3000
	v_lshlrev_b32_e32 v11, 13, v11
	v_and_or_b32 v133, v13, s20, v12
	s_mov_b64 s[20:21], 0x80
	s_add_i32 s81, s45, 0x18000
	v_bitop3_b32 v132, v14, v11, v10 bitop3:0xde
	v_lshl_add_u64 v[10:11], v[0:1], 0, s[20:21]
	s_mov_b32 m0, s81
	s_mov_b64 s[92:93], 0x20080
	s_add_i32 s84, s45, 0x1a000
	s_waitcnt vmcnt(4)
	s_barrier
	global_load_lds_dwordx4 v[10:11], off
	v_lshl_add_u64 v[0:1], v[0:1], 0, s[92:93]
	s_mov_b32 m0, s84
	s_add_i32 s85, s45, 0x8000
	global_load_lds_dwordx4 v[0:1], off
	v_lshl_add_u64 v[0:1], v[2:3], 0, s[20:21]
	s_mov_b32 m0, s85
	s_add_i32 s90, s45, 0xa000
	global_load_lds_dwordx4 v[0:1], off
	v_lshl_add_u64 v[0:1], v[2:3], 0, s[92:93]
	s_mov_b32 m0, s90
	s_add_i32 s91, s45, 0x1c000
	global_load_lds_dwordx4 v[0:1], off
	v_lshl_add_u64 v[0:1], v[4:5], 0, s[20:21]
	s_mov_b32 m0, s91
	s_movk_i32 s20, 0x3fc0
	global_load_lds_dwordx4 v[0:1], off
	v_lshl_add_u64 v[0:1], v[4:5], 0, s[92:93]
	s_add_i32 s92, s45, 0x1e000
	s_mov_b32 m0, s92
	s_nop 0
	global_load_lds_dwordx4 v[0:1], off
	v_mul_lo_u32 v0, v7, s20
	v_or_b32_e32 v0, v8, v0
	v_lshlrev_b32_e32 v1, 5, v6
	v_add3_u32 v0, v0, v9, v1
	s_add_u32 s20, s38, s22
	s_waitcnt vmcnt(6)
	v_ashrrev_i32_e32 v1, 31, v0
	s_addc_u32 s21, s39, s23
	v_lshlrev_b64 v[130:131], 1, v[0:1]
	s_add_u32 s22, s38, s24
	v_mov_b32_e32 v0, 0
	s_addc_u32 s23, s39, s25
	s_mov_b32 s24, -2
	v_mov_b32_e32 v1, v0
	v_mov_b32_e32 v2, v0
	v_mov_b32_e32 v3, v0
	v_mov_b32_e32 v4, v0
	v_mov_b32_e32 v5, v0
	v_mov_b32_e32 v6, v0
	v_mov_b32_e32 v7, v0
	v_mov_b32_e32 v8, v0
	v_mov_b32_e32 v9, v0
	v_mov_b32_e32 v10, v0
	v_mov_b32_e32 v11, v0
	v_mov_b32_e32 v12, v0
	v_mov_b32_e32 v13, v0
	v_mov_b32_e32 v14, v0
	v_mov_b32_e32 v15, v0
	v_mov_b32_e32 v16, v0
	v_mov_b32_e32 v17, v0
	v_mov_b32_e32 v18, v0
	v_mov_b32_e32 v19, v0
	v_mov_b32_e32 v20, v0
	v_mov_b32_e32 v21, v0
	v_mov_b32_e32 v22, v0
	v_mov_b32_e32 v23, v0
	v_mov_b32_e32 v24, v0
	v_mov_b32_e32 v25, v0
	v_mov_b32_e32 v26, v0
	v_mov_b32_e32 v27, v0
	v_mov_b32_e32 v28, v0
	v_mov_b32_e32 v29, v0
	v_mov_b32_e32 v30, v0
	v_mov_b32_e32 v31, v0
	v_mov_b32_e32 v32, v0
	v_mov_b32_e32 v33, v0
	v_mov_b32_e32 v34, v0
	v_mov_b32_e32 v35, v0
	v_mov_b32_e32 v36, v0
	v_mov_b32_e32 v37, v0
	v_mov_b32_e32 v38, v0
	v_mov_b32_e32 v39, v0
	v_mov_b32_e32 v40, v0
	v_mov_b32_e32 v41, v0
	v_mov_b32_e32 v42, v0
	v_mov_b32_e32 v43, v0
	v_mov_b32_e32 v44, v0
	v_mov_b32_e32 v45, v0
	v_mov_b32_e32 v46, v0
	v_mov_b32_e32 v47, v0
	v_mov_b32_e32 v48, v0
	v_mov_b32_e32 v49, v0
	v_mov_b32_e32 v50, v0
	v_mov_b32_e32 v51, v0
	v_mov_b32_e32 v52, v0
	v_mov_b32_e32 v53, v0
	v_mov_b32_e32 v54, v0
	v_mov_b32_e32 v55, v0
	v_mov_b32_e32 v56, v0
	v_mov_b32_e32 v57, v0
	v_mov_b32_e32 v58, v0
	v_mov_b32_e32 v59, v0
	v_mov_b32_e32 v60, v0
	v_mov_b32_e32 v61, v0
	v_mov_b32_e32 v62, v0
	v_mov_b32_e32 v63, v0
	v_mov_b32_e32 v64, v0
	v_mov_b32_e32 v65, v0
	v_mov_b32_e32 v66, v0
	v_mov_b32_e32 v67, v0
	v_mov_b32_e32 v68, v0
	v_mov_b32_e32 v69, v0
	v_mov_b32_e32 v70, v0
	v_mov_b32_e32 v71, v0
	v_mov_b32_e32 v72, v0
	v_mov_b32_e32 v73, v0
	v_mov_b32_e32 v74, v0
	v_mov_b32_e32 v75, v0
	v_mov_b32_e32 v76, v0
	v_mov_b32_e32 v77, v0
	v_mov_b32_e32 v78, v0
	v_mov_b32_e32 v79, v0
	v_mov_b32_e32 v80, v0
	v_mov_b32_e32 v81, v0
	v_mov_b32_e32 v82, v0
	v_mov_b32_e32 v83, v0
	v_mov_b32_e32 v84, v0
	v_mov_b32_e32 v85, v0
	v_mov_b32_e32 v86, v0
	v_mov_b32_e32 v87, v0
	v_mov_b32_e32 v88, v0
	v_mov_b32_e32 v89, v0
	v_mov_b32_e32 v90, v0
	v_mov_b32_e32 v91, v0
	v_mov_b32_e32 v92, v0
	v_mov_b32_e32 v93, v0
	v_mov_b32_e32 v94, v0
	v_mov_b32_e32 v95, v0
	v_mov_b32_e32 v96, v0
	v_mov_b32_e32 v97, v0
	v_mov_b32_e32 v98, v0
	v_mov_b32_e32 v99, v0
	v_mov_b32_e32 v100, v0
	v_mov_b32_e32 v101, v0
	v_mov_b32_e32 v102, v0
	v_mov_b32_e32 v103, v0
	v_mov_b32_e32 v104, v0
	v_mov_b32_e32 v105, v0
	v_mov_b32_e32 v106, v0
	v_mov_b32_e32 v107, v0
	v_mov_b32_e32 v108, v0
	v_mov_b32_e32 v109, v0
	v_mov_b32_e32 v110, v0
	v_mov_b32_e32 v111, v0
	v_mov_b32_e32 v112, v0
	v_mov_b32_e32 v113, v0
	v_mov_b32_e32 v114, v0
	v_mov_b32_e32 v115, v0
	v_mov_b32_e32 v116, v0
	v_mov_b32_e32 v117, v0
	v_mov_b32_e32 v118, v0
	v_mov_b32_e32 v119, v0
	v_mov_b32_e32 v120, v0
	v_mov_b32_e32 v121, v0
	v_mov_b32_e32 v122, v0
	v_mov_b32_e32 v123, v0
	v_mov_b32_e32 v124, v0
	v_mov_b32_e32 v125, v0
	v_mov_b32_e32 v126, v0
	v_mov_b32_e32 v127, v0
	s_barrier

; #define WAITV8(n) asm volatile("s_waitcnt vmcnt(" #n ")" ::: "memory")
; #define BAR8 __builtin_amdgcn_s_barrier()
;   DEV void tile_begin(int brow, char* shm, int tid) const { rstd_tile_begin(ss, brow, shm, tid); }
;   DEV void tile_begin(int brow, char* shm, int tid) const { rstd_tile_begin(ss, brow, shm, tid); }
; template <class Epi>
; DEV void gemm_tile8(char* shm, const u16* __restrict__ A, const u16* __restrict__ Bt, int K, int brow, int bcol, Epi& epi) {
;     ...
;   { int r_, c_; stage_rc<2>(wid * 1024 + lane * 16, r_, c_); so0 = r_ * K + c_; }
;   const int wids = __builtin_amdgcn_readfirstlane(wid);
;   const int la = lds_byte<2>(wr * 64 + fr, fq * 8), lb = lds_byte<2>(wc * 32 + fr, fq * 8);
;   f32x4 acc[2][2][4][2];
; #pragma unroll
;   for (int a = 0; a < 2; ++a)
; #pragma unroll
;     for (int b = 0; b < 2; ++b)
; #pragma unroll
;       for (int m = 0; m < 4; ++m)
; #pragma unroll
;         for (int n = 0; n < 2; ++n) acc[a][b][m][n] = f32x4{0.f, 0.f, 0.f, 0.f};
;   bf16x8 At[4][2], B0[2][2], B1[2][2];
;   const int nt = K / BK;
;   epi.tile_begin(brow, shm, tid);
;     ...
;   WAITV8(0);
;   STAGE8(SB8(0, 0), Bt, bcol, 0); STAGE8(SA8(0, 0), A, brow, 0);
;   STAGE8(SB8(0, 1), Bt, bcol + HALF, 0); STAGE8(SA8(0, 1), A, brow + HALF, 0);
;   if (wrs == 1) BAR8;
;   WAITV8(4); BAR8;
;   STAGE8(SB8(1, 0), Bt, bcol, 1); STAGE8(SA8(1, 0), A, brow, 1); STAGE8(SB8(1, 1), Bt, bcol + HALF, 1);
;   WAITV8(6); BAR8;
.LBB0_562:
	v_and_b32_e32 v12, 15, v10
	v_and_b32_e32 v13, 48, v10
	v_lshlrev_b32_e32 v10, 2, v10
	v_lshlrev_b32_e32 v12, 6, v12
	v_and_b32_e32 v10, 32, v10
	v_or_b32_e32 v14, v12, v13
	v_bitop3_b32 v12, v12, v10, v13 bitop3:0x36
	v_lshlrev_b32_e32 v13, 12, v6
	s_movk_i32 s18, 0x3000
	v_lshlrev_b32_e32 v11, 13, v11
	v_and_or_b32 v133, v13, s18, v12
	s_mov_b64 s[18:19], 0x80
	s_add_i32 s72, s43, 0x18000
	v_bitop3_b32 v132, v14, v11, v10 bitop3:0xde
	v_lshl_add_u64 v[10:11], v[0:1], 0, s[18:19]
	s_mov_b32 m0, s72
	s_mov_b64 s[90:91], 0x10080
	s_add_i32 s73, s43, 0x1a000
	s_waitcnt vmcnt(4)
	s_barrier
	global_load_lds_dwordx4 v[10:11], off
	v_lshl_add_u64 v[0:1], v[0:1], 0, s[90:91]
	s_mov_b32 m0, s73
	s_add_i32 s81, s43, 0x8000
	global_load_lds_dwordx4 v[0:1], off
	v_lshl_add_u64 v[0:1], v[2:3], 0, s[18:19]
	s_mov_b32 m0, s81
	s_add_i32 s84, s43, 0xa000
	global_load_lds_dwordx4 v[0:1], off
	v_lshl_add_u64 v[0:1], v[2:3], 0, s[90:91]
	s_mov_b32 m0, s84
	s_add_i32 s85, s43, 0x1c000
	global_load_lds_dwordx4 v[0:1], off
	v_lshl_add_u64 v[0:1], v[4:5], 0, s[18:19]
	s_mov_b32 m0, s85
	s_movk_i32 s18, 0x1fc0
	global_load_lds_dwordx4 v[0:1], off
	v_lshl_add_u64 v[0:1], v[4:5], 0, s[90:91]
	s_add_i32 s90, s43, 0x1e000
	s_mov_b32 m0, s90
	s_nop 0
	global_load_lds_dwordx4 v[0:1], off
	v_mul_lo_u32 v0, v7, s18
	v_or_b32_e32 v0, v8, v0
	v_lshlrev_b32_e32 v1, 5, v6
	v_add3_u32 v0, v0, v9, v1
	s_add_u32 s18, s38, s22
	s_waitcnt vmcnt(6)
	v_ashrrev_i32_e32 v1, 31, v0
	s_addc_u32 s19, s39, s23
	v_lshlrev_b64 v[130:131], 1, v[0:1]
	s_add_u32 s20, s38, s20
	v_mov_b32_e32 v0, 0
	s_addc_u32 s21, s39, s21
	s_mov_b32 s22, -2
	v_mov_b32_e32 v1, v0
	v_mov_b32_e32 v2, v0
	v_mov_b32_e32 v3, v0
	v_mov_b32_e32 v4, v0
	v_mov_b32_e32 v5, v0
	v_mov_b32_e32 v6, v0
	v_mov_b32_e32 v7, v0
	v_mov_b32_e32 v8, v0
	v_mov_b32_e32 v9, v0
	v_mov_b32_e32 v10, v0
	v_mov_b32_e32 v11, v0
	v_mov_b32_e32 v12, v0
	v_mov_b32_e32 v13, v0
	v_mov_b32_e32 v14, v0
	v_mov_b32_e32 v15, v0
	v_mov_b32_e32 v16, v0
	v_mov_b32_e32 v17, v0
	v_mov_b32_e32 v18, v0
	v_mov_b32_e32 v19, v0
	v_mov_b32_e32 v20, v0
	v_mov_b32_e32 v21, v0
	v_mov_b32_e32 v22, v0
	v_mov_b32_e32 v23, v0
	v_mov_b32_e32 v24, v0
	v_mov_b32_e32 v25, v0
	v_mov_b32_e32 v26, v0
	v_mov_b32_e32 v27, v0
	v_mov_b32_e32 v28, v0
	v_mov_b32_e32 v29, v0
	v_mov_b32_e32 v30, v0
	v_mov_b32_e32 v31, v0
	v_mov_b32_e32 v32, v0
	v_mov_b32_e32 v33, v0
	v_mov_b32_e32 v34, v0
	v_mov_b32_e32 v35, v0
	v_mov_b32_e32 v36, v0
	v_mov_b32_e32 v37, v0
	v_mov_b32_e32 v38, v0
	v_mov_b32_e32 v39, v0
	v_mov_b32_e32 v40, v0
	v_mov_b32_e32 v41, v0
	v_mov_b32_e32 v42, v0
	v_mov_b32_e32 v43, v0
	v_mov_b32_e32 v44, v0
	v_mov_b32_e32 v45, v0
	v_mov_b32_e32 v46, v0
	v_mov_b32_e32 v47, v0
	v_mov_b32_e32 v48, v0
	v_mov_b32_e32 v49, v0
	v_mov_b32_e32 v50, v0
	v_mov_b32_e32 v51, v0
	v_mov_b32_e32 v52, v0
	v_mov_b32_e32 v53, v0
	v_mov_b32_e32 v54, v0
	v_mov_b32_e32 v55, v0
	v_mov_b32_e32 v56, v0
	v_mov_b32_e32 v57, v0
	v_mov_b32_e32 v58, v0
	v_mov_b32_e32 v59, v0
	v_mov_b32_e32 v60, v0
	v_mov_b32_e32 v61, v0
	v_mov_b32_e32 v62, v0
	v_mov_b32_e32 v63, v0
	v_mov_b32_e32 v64, v0
	v_mov_b32_e32 v65, v0
	v_mov_b32_e32 v66, v0
	v_mov_b32_e32 v67, v0
	v_mov_b32_e32 v68, v0
	v_mov_b32_e32 v69, v0
	v_mov_b32_e32 v70, v0
	v_mov_b32_e32 v71, v0
	v_mov_b32_e32 v72, v0
	v_mov_b32_e32 v73, v0
	v_mov_b32_e32 v74, v0
	v_mov_b32_e32 v75, v0
	v_mov_b32_e32 v76, v0
	v_mov_b32_e32 v77, v0
	v_mov_b32_e32 v78, v0
	v_mov_b32_e32 v79, v0
	v_mov_b32_e32 v80, v0
	v_mov_b32_e32 v81, v0
	v_mov_b32_e32 v82, v0
	v_mov_b32_e32 v83, v0
	v_mov_b32_e32 v84, v0
	v_mov_b32_e32 v85, v0
	v_mov_b32_e32 v86, v0
	v_mov_b32_e32 v87, v0
	v_mov_b32_e32 v88, v0
	v_mov_b32_e32 v89, v0
	v_mov_b32_e32 v90, v0
	v_mov_b32_e32 v91, v0
	v_mov_b32_e32 v92, v0
	v_mov_b32_e32 v93, v0
	v_mov_b32_e32 v94, v0
	v_mov_b32_e32 v95, v0
	v_mov_b32_e32 v96, v0
	v_mov_b32_e32 v97, v0
	v_mov_b32_e32 v98, v0
	v_mov_b32_e32 v99, v0
	v_mov_b32_e32 v100, v0
	v_mov_b32_e32 v101, v0
	v_mov_b32_e32 v102, v0
	v_mov_b32_e32 v103, v0
	v_mov_b32_e32 v104, v0
	v_mov_b32_e32 v105, v0
	v_mov_b32_e32 v106, v0
	v_mov_b32_e32 v107, v0
	v_mov_b32_e32 v108, v0
	v_mov_b32_e32 v109, v0
	v_mov_b32_e32 v110, v0
	v_mov_b32_e32 v111, v0
	v_mov_b32_e32 v112, v0
	v_mov_b32_e32 v113, v0
	v_mov_b32_e32 v114, v0
	v_mov_b32_e32 v115, v0
	v_mov_b32_e32 v116, v0
	v_mov_b32_e32 v117, v0
	v_mov_b32_e32 v118, v0
	v_mov_b32_e32 v119, v0
	v_mov_b32_e32 v120, v0
	v_mov_b32_e32 v121, v0
	v_mov_b32_e32 v122, v0
	v_mov_b32_e32 v123, v0
	v_mov_b32_e32 v124, v0
	v_mov_b32_e32 v125, v0
	v_mov_b32_e32 v126, v0
	v_mov_b32_e32 v127, v0
	s_barrier

; #define WAITV8(n) asm volatile("s_waitcnt vmcnt(" #n ")" ::: "memory")
; #define BAR8 __builtin_amdgcn_s_barrier()
;   DEV void tile_begin(int brow, char* shm, int tid) const { rstd_tile_begin(ss, brow, shm, tid); }
;   DEV void tile_begin(int brow, char* shm, int tid) const { rstd_tile_begin(ss, brow, shm, tid); }
; template <class Epi>
; DEV void gemm_tile8(char* shm, const u16* __restrict__ A, const u16* __restrict__ Bt, int K, int brow, int bcol, Epi& epi) {
;     ...
;   { int r_, c_; stage_rc<2>(wid * 1024 + lane * 16, r_, c_); so0 = r_ * K + c_; }
;   const int wids = __builtin_amdgcn_readfirstlane(wid);
;   const int la = lds_byte<2>(wr * 64 + fr, fq * 8), lb = lds_byte<2>(wc * 32 + fr, fq * 8);
;   f32x4 acc[2][2][4][2];
; #pragma unroll
;   for (int a = 0; a < 2; ++a)
; #pragma unroll
;     for (int b = 0; b < 2; ++b)
; #pragma unroll
;       for (int m = 0; m < 4; ++m)
; #pragma unroll
;         for (int n = 0; n < 2; ++n) acc[a][b][m][n] = f32x4{0.f, 0.f, 0.f, 0.f};
;   bf16x8 At[4][2], B0[2][2], B1[2][2];
;   const int nt = K / BK;
;   epi.tile_begin(brow, shm, tid);
;     ...
;   WAITV8(0);
;   STAGE8(SB8(0, 0), Bt, bcol, 0); STAGE8(SA8(0, 0), A, brow, 0);
;   STAGE8(SB8(0, 1), Bt, bcol + HALF, 0); STAGE8(SA8(0, 1), A, brow + HALF, 0);
;   if (wrs == 1) BAR8;
;   WAITV8(4); BAR8;
;   STAGE8(SB8(1, 0), Bt, bcol, 1); STAGE8(SA8(1, 0), A, brow, 1); STAGE8(SB8(1, 1), Bt, bcol + HALF, 1);
;   WAITV8(6); BAR8;
.LBB0_598:
	v_and_b32_e32 v12, 15, v10
	v_and_b32_e32 v13, 48, v10
	v_lshlrev_b32_e32 v10, 2, v10
	v_lshlrev_b32_e32 v12, 6, v12
	v_and_b32_e32 v10, 32, v10
	v_or_b32_e32 v14, v12, v13
	v_bitop3_b32 v12, v12, v10, v13 bitop3:0x36
	v_lshlrev_b32_e32 v13, 12, v6
	s_movk_i32 s18, 0x3000
	v_lshlrev_b32_e32 v11, 13, v11
	v_and_or_b32 v133, v13, s18, v12
	s_mov_b64 s[18:19], 0x80
	s_add_i32 s72, s40, 0x18000
	v_bitop3_b32 v132, v14, v11, v10 bitop3:0xde
	v_lshl_add_u64 v[10:11], v[0:1], 0, s[18:19]
	s_mov_b32 m0, s72
	s_mov_b64 s[90:91], 0x10080
	s_add_i32 s73, s40, 0x1a000
	s_waitcnt vmcnt(4)
	s_barrier
	global_load_lds_dwordx4 v[10:11], off
	v_lshl_add_u64 v[0:1], v[0:1], 0, s[90:91]
	s_mov_b32 m0, s73
	s_add_i32 s81, s40, 0x8000
	global_load_lds_dwordx4 v[0:1], off
	v_lshl_add_u64 v[0:1], v[2:3], 0, s[18:19]
	s_mov_b32 m0, s81
	s_add_i32 s84, s40, 0xa000
	global_load_lds_dwordx4 v[0:1], off
	v_lshl_add_u64 v[0:1], v[2:3], 0, s[90:91]
	s_mov_b32 m0, s84
	s_add_i32 s85, s40, 0x1c000
	global_load_lds_dwordx4 v[0:1], off
	v_lshl_add_u64 v[0:1], v[4:5], 0, s[18:19]
	s_mov_b32 m0, s85
	s_movk_i32 s18, 0x1fc0
	global_load_lds_dwordx4 v[0:1], off
	v_lshl_add_u64 v[0:1], v[4:5], 0, s[90:91]
	s_add_i32 s90, s40, 0x1e000
	s_mov_b32 m0, s90
	s_nop 0
	global_load_lds_dwordx4 v[0:1], off
	v_mul_lo_u32 v0, v7, s18
	v_or_b32_e32 v0, v8, v0
	v_lshlrev_b32_e32 v1, 5, v6
	v_add3_u32 v0, v0, v9, v1
	s_add_u32 s18, s38, s22
	s_waitcnt vmcnt(6)
	v_ashrrev_i32_e32 v1, 31, v0
	s_addc_u32 s19, s39, s23
	v_lshlrev_b64 v[130:131], 1, v[0:1]
	s_add_u32 s20, s38, s20
	v_mov_b32_e32 v0, 0
	s_addc_u32 s21, s39, s21
	s_mov_b32 s22, -2
	v_mov_b32_e32 v1, v0
	v_mov_b32_e32 v2, v0
	v_mov_b32_e32 v3, v0
	v_mov_b32_e32 v4, v0
	v_mov_b32_e32 v5, v0
	v_mov_b32_e32 v6, v0
	v_mov_b32_e32 v7, v0
	v_mov_b32_e32 v8, v0
	v_mov_b32_e32 v9, v0
	v_mov_b32_e32 v10, v0
	v_mov_b32_e32 v11, v0
	v_mov_b32_e32 v12, v0
	v_mov_b32_e32 v13, v0
	v_mov_b32_e32 v14, v0
	v_mov_b32_e32 v15, v0
	v_mov_b32_e32 v16, v0
	v_mov_b32_e32 v17, v0
	v_mov_b32_e32 v18, v0
	v_mov_b32_e32 v19, v0
	v_mov_b32_e32 v20, v0
	v_mov_b32_e32 v21, v0
	v_mov_b32_e32 v22, v0
	v_mov_b32_e32 v23, v0
	v_mov_b32_e32 v24, v0
	v_mov_b32_e32 v25, v0
	v_mov_b32_e32 v26, v0
	v_mov_b32_e32 v27, v0
	v_mov_b32_e32 v28, v0
	v_mov_b32_e32 v29, v0
	v_mov_b32_e32 v30, v0
	v_mov_b32_e32 v31, v0
	v_mov_b32_e32 v32, v0
	v_mov_b32_e32 v33, v0
	v_mov_b32_e32 v34, v0
	v_mov_b32_e32 v35, v0
	v_mov_b32_e32 v36, v0
	v_mov_b32_e32 v37, v0
	v_mov_b32_e32 v38, v0
	v_mov_b32_e32 v39, v0
	v_mov_b32_e32 v40, v0
	v_mov_b32_e32 v41, v0
	v_mov_b32_e32 v42, v0
	v_mov_b32_e32 v43, v0
	v_mov_b32_e32 v44, v0
	v_mov_b32_e32 v45, v0
	v_mov_b32_e32 v46, v0
	v_mov_b32_e32 v47, v0
	v_mov_b32_e32 v48, v0
	v_mov_b32_e32 v49, v0
	v_mov_b32_e32 v50, v0
	v_mov_b32_e32 v51, v0
	v_mov_b32_e32 v52, v0
	v_mov_b32_e32 v53, v0
	v_mov_b32_e32 v54, v0
	v_mov_b32_e32 v55, v0
	v_mov_b32_e32 v56, v0
	v_mov_b32_e32 v57, v0
	v_mov_b32_e32 v58, v0
	v_mov_b32_e32 v59, v0
	v_mov_b32_e32 v60, v0
	v_mov_b32_e32 v61, v0
	v_mov_b32_e32 v62, v0
	v_mov_b32_e32 v63, v0
	v_mov_b32_e32 v64, v0
	v_mov_b32_e32 v65, v0
	v_mov_b32_e32 v66, v0
	v_mov_b32_e32 v67, v0
	v_mov_b32_e32 v68, v0
	v_mov_b32_e32 v69, v0
	v_mov_b32_e32 v70, v0
	v_mov_b32_e32 v71, v0
	v_mov_b32_e32 v72, v0
	v_mov_b32_e32 v73, v0
	v_mov_b32_e32 v74, v0
	v_mov_b32_e32 v75, v0
	v_mov_b32_e32 v76, v0
	v_mov_b32_e32 v77, v0
	v_mov_b32_e32 v78, v0
	v_mov_b32_e32 v79, v0
	v_mov_b32_e32 v80, v0
	v_mov_b32_e32 v81, v0
	v_mov_b32_e32 v82, v0
	v_mov_b32_e32 v83, v0
	v_mov_b32_e32 v84, v0
	v_mov_b32_e32 v85, v0
	v_mov_b32_e32 v86, v0
	v_mov_b32_e32 v87, v0
	v_mov_b32_e32 v88, v0
	v_mov_b32_e32 v89, v0
	v_mov_b32_e32 v90, v0
	v_mov_b32_e32 v91, v0
	v_mov_b32_e32 v92, v0
	v_mov_b32_e32 v93, v0
	v_mov_b32_e32 v94, v0
	v_mov_b32_e32 v95, v0
	v_mov_b32_e32 v96, v0
	v_mov_b32_e32 v97, v0
	v_mov_b32_e32 v98, v0
	v_mov_b32_e32 v99, v0
	v_mov_b32_e32 v100, v0
	v_mov_b32_e32 v101, v0
	v_mov_b32_e32 v102, v0
	v_mov_b32_e32 v103, v0
	v_mov_b32_e32 v104, v0
	v_mov_b32_e32 v105, v0
	v_mov_b32_e32 v106, v0
	v_mov_b32_e32 v107, v0
	v_mov_b32_e32 v108, v0
	v_mov_b32_e32 v109, v0
	v_mov_b32_e32 v110, v0
	v_mov_b32_e32 v111, v0
	v_mov_b32_e32 v112, v0
	v_mov_b32_e32 v113, v0
	v_mov_b32_e32 v114, v0
	v_mov_b32_e32 v115, v0
	v_mov_b32_e32 v116, v0
	v_mov_b32_e32 v117, v0
	v_mov_b32_e32 v118, v0
	v_mov_b32_e32 v119, v0
	v_mov_b32_e32 v120, v0
	v_mov_b32_e32 v121, v0
	v_mov_b32_e32 v122, v0
	v_mov_b32_e32 v123, v0
	v_mov_b32_e32 v124, v0
	v_mov_b32_e32 v125, v0
	v_mov_b32_e32 v126, v0
	v_mov_b32_e32 v127, v0
	s_barrier

; #define WAITV8(n) asm volatile("s_waitcnt vmcnt(" #n ")" ::: "memory")
; #define BAR8 __builtin_amdgcn_s_barrier()
;   DEV void tile_begin(int brow, char* shm, int tid) const { rstd_tile_begin(ss, brow, shm, tid); }
;   DEV void tile_begin(int brow, char* shm, int tid) const { rstd_tile_begin(ss, brow, shm, tid); }
; template <class Epi>
; DEV void gemm_tile8(char* shm, const u16* __restrict__ A, const u16* __restrict__ Bt, int K, int brow, int bcol, Epi& epi) {
;     ...
;   { int r_, c_; stage_rc<2>(wid * 1024 + lane * 16, r_, c_); so0 = r_ * K + c_; }
;   const int wids = __builtin_amdgcn_readfirstlane(wid);
;   const int la = lds_byte<2>(wr * 64 + fr, fq * 8), lb = lds_byte<2>(wc * 32 + fr, fq * 8);
;   f32x4 acc[2][2][4][2];
; #pragma unroll
;   for (int a = 0; a < 2; ++a)
; #pragma unroll
;     for (int b = 0; b < 2; ++b)
; #pragma unroll
;       for (int m = 0; m < 4; ++m)
; #pragma unroll
;         for (int n = 0; n < 2; ++n) acc[a][b][m][n] = f32x4{0.f, 0.f, 0.f, 0.f};
;   bf16x8 At[4][2], B0[2][2], B1[2][2];
;   const int nt = K / BK;
;   epi.tile_begin(brow, shm, tid);
;     ...
;   WAITV8(0);
;   STAGE8(SB8(0, 0), Bt, bcol, 0); STAGE8(SA8(0, 0), A, brow, 0);
;   STAGE8(SB8(0, 1), Bt, bcol + HALF, 0); STAGE8(SA8(0, 1), A, brow + HALF, 0);
;   if (wrs == 1) BAR8;
;   WAITV8(4); BAR8;
;   STAGE8(SB8(1, 0), Bt, bcol, 1); STAGE8(SA8(1, 0), A, brow, 1); STAGE8(SB8(1, 1), Bt, bcol + HALF, 1);
;   WAITV8(6); BAR8;
.LBB0_906:
	v_and_b32_e32 v12, 15, v10
	v_and_b32_e32 v13, 48, v10
	v_lshlrev_b32_e32 v10, 2, v10
	v_lshlrev_b32_e32 v12, 6, v12
	v_and_b32_e32 v10, 32, v10
	v_or_b32_e32 v14, v12, v13
	v_bitop3_b32 v12, v12, v10, v13 bitop3:0x36
	v_lshlrev_b32_e32 v13, 12, v6
	s_movk_i32 s45, 0x3000
	v_lshlrev_b32_e32 v11, 13, v11
	v_and_or_b32 v133, v13, s45, v12
	s_mov_b64 s[72:73], 0x80
	s_add_i32 s45, s13, 0x18000
	v_bitop3_b32 v132, v14, v11, v10 bitop3:0xde
	v_lshl_add_u64 v[10:11], v[0:1], 0, s[72:73]
	s_mov_b32 m0, s45
	s_mov_b64 s[90:91], 0x20080
	s_add_i32 s54, s13, 0x1a000
	s_waitcnt vmcnt(4)
	s_barrier
	global_load_lds_dwordx4 v[10:11], off
	v_lshl_add_u64 v[0:1], v[0:1], 0, s[90:91]
	s_mov_b32 m0, s54
	s_add_i32 s55, s13, 0x8000
	global_load_lds_dwordx4 v[0:1], off
	v_lshl_add_u64 v[0:1], v[2:3], 0, s[72:73]
	s_mov_b32 m0, s55
	s_add_i32 s70, s13, 0xa000
	global_load_lds_dwordx4 v[0:1], off
	v_lshl_add_u64 v[0:1], v[2:3], 0, s[90:91]
	s_mov_b32 m0, s70
	s_add_i32 s71, s13, 0x1c000
	global_load_lds_dwordx4 v[0:1], off
	v_lshl_add_u64 v[0:1], v[4:5], 0, s[72:73]
	s_mov_b32 m0, s71
	s_add_i32 s72, s13, 0x1e000
	global_load_lds_dwordx4 v[0:1], off
	v_lshl_add_u64 v[0:1], v[4:5], 0, s[90:91]
	s_mov_b32 m0, s72
	s_movk_i32 s73, 0x3fc0
	global_load_lds_dwordx4 v[0:1], off
	v_mul_lo_u32 v0, v7, s73
	v_or_b32_e32 v0, v8, v0
	v_lshlrev_b32_e32 v1, 5, v6
	v_add3_u32 v0, v0, v9, v1
	s_waitcnt vmcnt(6)
	v_ashrrev_i32_e32 v1, 31, v0
	v_lshlrev_b64 v[130:131], 1, v[0:1]
	v_mov_b32_e32 v0, 0
	s_mov_b32 s73, -2
	v_mov_b32_e32 v1, v0
	v_mov_b32_e32 v2, v0
	v_mov_b32_e32 v3, v0
	v_mov_b32_e32 v4, v0
	v_mov_b32_e32 v5, v0
	v_mov_b32_e32 v6, v0
	v_mov_b32_e32 v7, v0
	v_mov_b32_e32 v8, v0
	v_mov_b32_e32 v9, v0
	v_mov_b32_e32 v10, v0
	v_mov_b32_e32 v11, v0
	v_mov_b32_e32 v12, v0
	v_mov_b32_e32 v13, v0
	v_mov_b32_e32 v14, v0
	v_mov_b32_e32 v15, v0
	v_mov_b32_e32 v16, v0
	v_mov_b32_e32 v17, v0
	v_mov_b32_e32 v18, v0
	v_mov_b32_e32 v19, v0
	v_mov_b32_e32 v20, v0
	v_mov_b32_e32 v21, v0
	v_mov_b32_e32 v22, v0
	v_mov_b32_e32 v23, v0
	v_mov_b32_e32 v24, v0
	v_mov_b32_e32 v25, v0
	v_mov_b32_e32 v26, v0
	v_mov_b32_e32 v27, v0
	v_mov_b32_e32 v28, v0
	v_mov_b32_e32 v29, v0
	v_mov_b32_e32 v30, v0
	v_mov_b32_e32 v31, v0
	v_mov_b32_e32 v32, v0
	v_mov_b32_e32 v33, v0
	v_mov_b32_e32 v34, v0
	v_mov_b32_e32 v35, v0
	v_mov_b32_e32 v36, v0
	v_mov_b32_e32 v37, v0
	v_mov_b32_e32 v38, v0
	v_mov_b32_e32 v39, v0
	v_mov_b32_e32 v40, v0
	v_mov_b32_e32 v41, v0
	v_mov_b32_e32 v42, v0
	v_mov_b32_e32 v43, v0
	v_mov_b32_e32 v44, v0
	v_mov_b32_e32 v45, v0
	v_mov_b32_e32 v46, v0
	v_mov_b32_e32 v47, v0
	v_mov_b32_e32 v48, v0
	v_mov_b32_e32 v49, v0
	v_mov_b32_e32 v50, v0
	v_mov_b32_e32 v51, v0
	v_mov_b32_e32 v52, v0
	v_mov_b32_e32 v53, v0
	v_mov_b32_e32 v54, v0
	v_mov_b32_e32 v55, v0
	v_mov_b32_e32 v56, v0
	v_mov_b32_e32 v57, v0
	v_mov_b32_e32 v58, v0
	v_mov_b32_e32 v59, v0
	v_mov_b32_e32 v60, v0
	v_mov_b32_e32 v61, v0
	v_mov_b32_e32 v62, v0
	v_mov_b32_e32 v63, v0
	v_mov_b32_e32 v64, v0
	v_mov_b32_e32 v65, v0
	v_mov_b32_e32 v66, v0
	v_mov_b32_e32 v67, v0
	v_mov_b32_e32 v68, v0
	v_mov_b32_e32 v69, v0
	v_mov_b32_e32 v70, v0
	v_mov_b32_e32 v71, v0
	v_mov_b32_e32 v72, v0
	v_mov_b32_e32 v73, v0
	v_mov_b32_e32 v74, v0
	v_mov_b32_e32 v75, v0
	v_mov_b32_e32 v76, v0
	v_mov_b32_e32 v77, v0
	v_mov_b32_e32 v78, v0
	v_mov_b32_e32 v79, v0
	v_mov_b32_e32 v80, v0
	v_mov_b32_e32 v81, v0
	v_mov_b32_e32 v82, v0
	v_mov_b32_e32 v83, v0
	v_mov_b32_e32 v84, v0
	v_mov_b32_e32 v85, v0
	v_mov_b32_e32 v86, v0
	v_mov_b32_e32 v87, v0
	v_mov_b32_e32 v88, v0
	v_mov_b32_e32 v89, v0
	v_mov_b32_e32 v90, v0
	v_mov_b32_e32 v91, v0
	v_mov_b32_e32 v92, v0
	v_mov_b32_e32 v93, v0
	v_mov_b32_e32 v94, v0
	v_mov_b32_e32 v95, v0
	v_mov_b32_e32 v96, v0
	v_mov_b32_e32 v97, v0
	v_mov_b32_e32 v98, v0
	v_mov_b32_e32 v99, v0
	v_mov_b32_e32 v100, v0
	v_mov_b32_e32 v101, v0
	v_mov_b32_e32 v102, v0
	v_mov_b32_e32 v103, v0
	v_mov_b32_e32 v104, v0
	v_mov_b32_e32 v105, v0
	v_mov_b32_e32 v106, v0
	v_mov_b32_e32 v107, v0
	v_mov_b32_e32 v108, v0
	v_mov_b32_e32 v109, v0
	v_mov_b32_e32 v110, v0
	v_mov_b32_e32 v111, v0
	v_mov_b32_e32 v112, v0
	v_mov_b32_e32 v113, v0
	v_mov_b32_e32 v114, v0
	v_mov_b32_e32 v115, v0
	v_mov_b32_e32 v116, v0
	v_mov_b32_e32 v117, v0
	v_mov_b32_e32 v118, v0
	v_mov_b32_e32 v119, v0
	v_mov_b32_e32 v120, v0
	v_mov_b32_e32 v121, v0
	v_mov_b32_e32 v122, v0
	v_mov_b32_e32 v123, v0
	v_mov_b32_e32 v124, v0
	v_mov_b32_e32 v125, v0
	v_mov_b32_e32 v126, v0
	v_mov_b32_e32 v127, v0
	s_barrier
